# strategy 7: FFN-in K loops, LDS-DMA loads in (SGPR base + 32-bit VGPR offset) form where the address temporary is dead afterwards (64-bit VALU adds removed)
# speedup vs baseline: 1.0020x; 1.0016x over previous
.LBB0_219:
	s_ashr_i32 s17, s16, 31
	s_lshl_b64 s[18:19], s[16:17], 19
	s_add_u32 s18, s42, s18
	s_addc_u32 s19, s43, s19
	s_and_b64 s[20:21], s[2:3], exec
	s_cselect_b32 s17, s19, s25
	s_cselect_b32 s65, s18, s24
	s_ashr_i32 s15, s14, 31
	s_lshl_b64 s[20:21], s[14:15], 19
	s_add_u32 s20, s40, s20
	s_addc_u32 s21, s41, s21
	s_and_b64 s[34:35], s[2:3], exec
	s_cselect_b32 s15, s21, s27
	s_cselect_b32 s66, s20, s26
	s_add_u32 s24, s24, 0x40080
	s_addc_u32 s25, s25, 0
	s_add_u32 s67, s26, 0x100
	s_addc_u32 s68, s27, 0
	s_mov_b32 s69, -2
	s_waitcnt lgkmcnt(0)
	ds_read_b128 v[104:107], v171
	ds_read_b128 v[108:111], v171 offset:1024
	ds_read_b128 v[112:115], v171 offset:2048
	ds_read_b128 v[116:119], v171 offset:3072
	ds_read_b128 v[160:163], v172
	ds_read_b128 v[164:167], v172 offset:1024
	ds_read_b128 v[178:181], v172 offset:2048
	ds_read_b128 v[182:185], v172 offset:3072
	s_add_u32 s26, s24, 0xfffc0080
	s_addc_u32 s27, s25, -1
	s_cmp_eq_u32 s69, 12
	s_cselect_b32 s35, s17, s27
	s_cselect_b32 s34, s65, s26
	s_cselect_b32 s27, s15, s68
	s_cselect_b32 s26, s66, s67
	v_lshl_add_u64 v[202:203], s[24:25], 0, v[152:153]
	s_add_i32 m0, s23, 0xc000
	ds_read_b128 v[186:189], v173
	ds_read_b128 v[190:193], v173 offset:1024
	ds_read_b128 v[194:197], v173 offset:2048
	ds_read_b128 v[198:201], v173 offset:3072
	ds_read_b128 v[206:209], v173 offset:4096
	ds_read_b128 v[210:213], v173 offset:5120
	ds_read_b128 v[214:217], v173 offset:6144
	ds_read_b128 v[218:221], v173 offset:7168
	global_load_lds_dwordx4 v[202:203], off
	v_lshl_add_u64 v[202:203], s[24:25], 0, v[154:155]
	s_add_i32 m0, s23, 0xe000
	s_nop 0
	global_load_lds_dwordx4 v[202:203], off
	s_waitcnt vmcnt(8)
	s_waitcnt lgkmcnt(0)
	s_barrier
	s_waitcnt lgkmcnt(0)
	v_mfma_f32_16x16x32_f16 v[140:143], v[104:107], v[186:189], 0
	v_mfma_f32_16x16x32_f16 v[136:139], v[112:115], v[186:189], 0
	v_mfma_f32_16x16x32_f16 v[124:127], v[104:107], v[194:197], 0
	v_mfma_f32_16x16x32_f16 v[120:123], v[112:115], v[194:197], 0
	v_mfma_f32_16x16x32_f16 v[92:95], v[104:107], v[206:209], 0
	v_mfma_f32_16x16x32_f16 v[88:91], v[112:115], v[206:209], 0
	v_mfma_f32_16x16x32_f16 v[76:79], v[104:107], v[214:217], 0
	v_mfma_f32_16x16x32_f16 v[72:75], v[112:115], v[214:217], 0
	v_mfma_f32_16x16x32_f16 v[140:143], v[108:111], v[190:193], v[140:143]
	v_mfma_f32_16x16x32_f16 v[136:139], v[116:119], v[190:193], v[136:139]
	v_mfma_f32_16x16x32_f16 v[124:127], v[108:111], v[198:201], v[124:127]
	v_mfma_f32_16x16x32_f16 v[120:123], v[116:119], v[198:201], v[120:123]
	v_mfma_f32_16x16x32_f16 v[92:95], v[108:111], v[210:213], v[92:95]
	v_mfma_f32_16x16x32_f16 v[88:91], v[116:119], v[210:213], v[88:91]
	v_mfma_f32_16x16x32_f16 v[76:79], v[108:111], v[218:221], v[76:79]
	v_mfma_f32_16x16x32_f16 v[72:75], v[116:119], v[218:221], v[72:75]
	v_mfma_f32_16x16x32_f16 v[132:135], v[160:163], v[186:189], 0
	v_mfma_f32_16x16x32_f16 v[128:131], v[178:181], v[186:189], 0
	v_mfma_f32_16x16x32_f16 v[100:103], v[160:163], v[194:197], 0
	v_mfma_f32_16x16x32_f16 v[96:99], v[178:181], v[194:197], 0
	v_mfma_f32_16x16x32_f16 v[84:87], v[160:163], v[206:209], 0
	v_mfma_f32_16x16x32_f16 v[80:83], v[178:181], v[206:209], 0
	v_mfma_f32_16x16x32_f16 v[68:71], v[160:163], v[214:217], 0
	v_mfma_f32_16x16x32_f16 v[64:67], v[178:181], v[214:217], 0
	v_mfma_f32_16x16x32_f16 v[132:135], v[164:167], v[190:193], v[132:135]
	v_mfma_f32_16x16x32_f16 v[128:131], v[182:185], v[190:193], v[128:131]
	v_mfma_f32_16x16x32_f16 v[100:103], v[164:167], v[198:201], v[100:103]
	v_mfma_f32_16x16x32_f16 v[96:99], v[182:185], v[198:201], v[96:99]
	v_mfma_f32_16x16x32_f16 v[84:87], v[164:167], v[210:213], v[84:87]
	v_mfma_f32_16x16x32_f16 v[80:83], v[182:185], v[210:213], v[80:83]
	v_mfma_f32_16x16x32_f16 v[68:71], v[164:167], v[218:221], v[68:71]
	v_mfma_f32_16x16x32_f16 v[64:67], v[182:185], v[218:221], v[64:67]
	s_barrier
	s_add_i32 s70, s60, s44
	v_lshl_add_u64 v[202:203], s[26:27], 0, v[146:147]
	s_mov_b32 m0, s70
	ds_read_b128 v[186:189], v173 offset:16384
	ds_read_b128 v[190:193], v173 offset:17408
	ds_read_b128 v[194:197], v173 offset:18432
	ds_read_b128 v[198:201], v173 offset:19456
	ds_read_b128 v[206:209], v173 offset:20480
	ds_read_b128 v[210:213], v173 offset:21504
	ds_read_b128 v[214:217], v173 offset:22528
	ds_read_b128 v[218:221], v173 offset:23552
	global_load_lds_dwordx4 v[202:203], off
	s_add_i32 m0, s70, 0x2000
	s_add_u32 s70, s26, 0x40000
	v_lshl_add_u64 v[222:223], s[26:27], 0, v[150:151]
	s_addc_u32 s71, s27, 0
	s_add_i32 s72, s61, s44
	global_load_lds_dwordx4 v[222:223], off
	v_lshl_add_u64 v[224:225], s[70:71], 0, v[146:147]
	s_mov_b32 m0, s72
	v_lshl_add_u64 v[226:227], s[34:35], 0, v[148:149]
	global_load_lds_dwordx4 v[224:225], off
	v_lshl_add_u64 v[224:225], s[70:71], 0, v[150:151]
	s_add_i32 m0, s72, 0x2000
	s_nop 0
	global_load_lds_dwordx4 v[224:225], off
	v_lshl_add_u64 v[224:225], s[34:35], 0, v[144:145]
	s_mov_b32 m0, s23
	s_nop 0
	global_load_lds_dwordx4 v[224:225], off
	s_mov_b32 m0, s45
	s_nop 0
	global_load_lds_dwordx4 v[226:227], off
	s_waitcnt vmcnt(8)
	s_waitcnt lgkmcnt(0)
	s_barrier
	s_waitcnt lgkmcnt(0)
	v_mfma_f32_16x16x32_f16 v[60:63], v[104:107], v[186:189], 0
	v_mfma_f32_16x16x32_f16 v[56:59], v[112:115], v[186:189], 0
	v_mfma_f32_16x16x32_f16 v[44:47], v[104:107], v[194:197], 0
	v_mfma_f32_16x16x32_f16 v[40:43], v[112:115], v[194:197], 0
	v_mfma_f32_16x16x32_f16 v[28:31], v[104:107], v[206:209], 0
	v_mfma_f32_16x16x32_f16 v[24:27], v[112:115], v[206:209], 0
	v_mfma_f32_16x16x32_f16 v[12:15], v[104:107], v[214:217], 0
	v_mfma_f32_16x16x32_f16 v[8:11], v[112:115], v[214:217], 0
	v_mfma_f32_16x16x32_f16 v[60:63], v[108:111], v[190:193], v[60:63]
	v_mfma_f32_16x16x32_f16 v[56:59], v[116:119], v[190:193], v[56:59]
	v_mfma_f32_16x16x32_f16 v[44:47], v[108:111], v[198:201], v[44:47]
	v_mfma_f32_16x16x32_f16 v[40:43], v[116:119], v[198:201], v[40:43]
	v_mfma_f32_16x16x32_f16 v[28:31], v[108:111], v[210:213], v[28:31]
	v_mfma_f32_16x16x32_f16 v[24:27], v[116:119], v[210:213], v[24:27]
	v_mfma_f32_16x16x32_f16 v[12:15], v[108:111], v[218:221], v[12:15]
	v_mfma_f32_16x16x32_f16 v[8:11], v[116:119], v[218:221], v[8:11]
	v_mfma_f32_16x16x32_f16 v[52:55], v[160:163], v[186:189], 0
	v_mfma_f32_16x16x32_f16 v[48:51], v[178:181], v[186:189], 0
	v_mfma_f32_16x16x32_f16 v[36:39], v[160:163], v[194:197], 0
	v_mfma_f32_16x16x32_f16 v[32:35], v[178:181], v[194:197], 0
	v_mfma_f32_16x16x32_f16 v[20:23], v[160:163], v[206:209], 0
	v_mfma_f32_16x16x32_f16 v[16:19], v[178:181], v[206:209], 0
	v_mfma_f32_16x16x32_f16 v[4:7], v[160:163], v[214:217], 0
	v_mfma_f32_16x16x32_f16 v[0:3], v[178:181], v[214:217], 0
	v_mfma_f32_16x16x32_f16 v[52:55], v[164:167], v[190:193], v[52:55]
	v_mfma_f32_16x16x32_f16 v[48:51], v[182:185], v[190:193], v[48:51]
	v_mfma_f32_16x16x32_f16 v[36:39], v[164:167], v[198:201], v[36:39]
	v_mfma_f32_16x16x32_f16 v[32:35], v[182:185], v[198:201], v[32:35]
	v_mfma_f32_16x16x32_f16 v[20:23], v[164:167], v[210:213], v[20:23]
	v_mfma_f32_16x16x32_f16 v[16:19], v[182:185], v[210:213], v[16:19]
	v_mfma_f32_16x16x32_f16 v[4:7], v[164:167], v[218:221], v[4:7]
	v_mfma_f32_16x16x32_f16 v[0:3], v[182:185], v[218:221], v[0:3]
	s_barrier
	s_add_i32 s70, 0, 0x18000
	s_add_i32 s71, 0, 0x1c000
	v_add_u32_e32 v116, s70, v169
	v_add_u32_e32 v177, s71, v169
	ds_read_b128 v[104:107], v116
	ds_read_b128 v[108:111], v116 offset:1024
	ds_read_b128 v[112:115], v116 offset:2048
	ds_read_b128 v[116:119], v116 offset:3072
	ds_read_b128 v[160:163], v177
	ds_read_b128 v[164:167], v177 offset:1024
	ds_read_b128 v[178:181], v177 offset:2048
	ds_read_b128 v[182:185], v177 offset:3072
	s_add_u32 s34, s34, 0x40000
	s_addc_u32 s35, s35, 0
	s_mov_b32 m0, s46
	v_lshl_add_u64 v[228:229], s[34:35], 0, v[144:145]
	ds_read_b128 v[186:189], v173 offset:32768
	ds_read_b128 v[190:193], v173 offset:33792
	ds_read_b128 v[194:197], v173 offset:34816
	ds_read_b128 v[198:201], v173 offset:35840
	ds_read_b128 v[206:209], v173 offset:36864
	ds_read_b128 v[210:213], v173 offset:37888
	ds_read_b128 v[214:217], v173 offset:38912
	ds_read_b128 v[218:221], v173 offset:39936
	global_load_lds_dwordx4 v[228:229], off
	v_lshl_add_u64 v[228:229], s[34:35], 0, v[148:149]
	s_mov_b32 m0, s47
	s_nop 0
	global_load_lds_dwordx4 v[228:229], off
	s_waitcnt vmcnt(8)
	s_waitcnt lgkmcnt(0)
	s_barrier
	s_waitcnt lgkmcnt(0)
	v_mfma_f32_16x16x32_f16 v[140:143], v[104:107], v[186:189], v[140:143]
	v_mfma_f32_16x16x32_f16 v[136:139], v[112:115], v[186:189], v[136:139]
	v_mfma_f32_16x16x32_f16 v[124:127], v[104:107], v[194:197], v[124:127]
	v_mfma_f32_16x16x32_f16 v[120:123], v[112:115], v[194:197], v[120:123]
	v_mfma_f32_16x16x32_f16 v[92:95], v[104:107], v[206:209], v[92:95]
	v_mfma_f32_16x16x32_f16 v[88:91], v[112:115], v[206:209], v[88:91]
	v_mfma_f32_16x16x32_f16 v[76:79], v[104:107], v[214:217], v[76:79]
	v_mfma_f32_16x16x32_f16 v[72:75], v[112:115], v[214:217], v[72:75]
	v_mfma_f32_16x16x32_f16 v[140:143], v[108:111], v[190:193], v[140:143]
	v_mfma_f32_16x16x32_f16 v[136:139], v[116:119], v[190:193], v[136:139]
	v_mfma_f32_16x16x32_f16 v[124:127], v[108:111], v[198:201], v[124:127]
	v_mfma_f32_16x16x32_f16 v[120:123], v[116:119], v[198:201], v[120:123]
	v_mfma_f32_16x16x32_f16 v[92:95], v[108:111], v[210:213], v[92:95]
	v_mfma_f32_16x16x32_f16 v[88:91], v[116:119], v[210:213], v[88:91]
	v_mfma_f32_16x16x32_f16 v[76:79], v[108:111], v[218:221], v[76:79]
	v_mfma_f32_16x16x32_f16 v[72:75], v[116:119], v[218:221], v[72:75]
	v_mfma_f32_16x16x32_f16 v[132:135], v[160:163], v[186:189], v[132:135]
	v_mfma_f32_16x16x32_f16 v[128:131], v[178:181], v[186:189], v[128:131]
	v_mfma_f32_16x16x32_f16 v[100:103], v[160:163], v[194:197], v[100:103]
	v_mfma_f32_16x16x32_f16 v[96:99], v[178:181], v[194:197], v[96:99]
	v_mfma_f32_16x16x32_f16 v[84:87], v[160:163], v[206:209], v[84:87]
	v_mfma_f32_16x16x32_f16 v[80:83], v[178:181], v[206:209], v[80:83]
	v_mfma_f32_16x16x32_f16 v[68:71], v[160:163], v[214:217], v[68:71]
	v_mfma_f32_16x16x32_f16 v[64:67], v[178:181], v[214:217], v[64:67]
	v_mfma_f32_16x16x32_f16 v[132:135], v[164:167], v[190:193], v[132:135]
	v_mfma_f32_16x16x32_f16 v[128:131], v[182:185], v[190:193], v[128:131]
	v_mfma_f32_16x16x32_f16 v[100:103], v[164:167], v[198:201], v[100:103]
	v_mfma_f32_16x16x32_f16 v[96:99], v[182:185], v[198:201], v[96:99]
	v_mfma_f32_16x16x32_f16 v[84:87], v[164:167], v[210:213], v[84:87]
	v_mfma_f32_16x16x32_f16 v[80:83], v[182:185], v[210:213], v[80:83]
	v_mfma_f32_16x16x32_f16 v[68:71], v[164:167], v[218:221], v[68:71]
	v_mfma_f32_16x16x32_f16 v[64:67], v[182:185], v[218:221], v[64:67]
	s_barrier
	s_add_i32 s34, s70, s44
	v_lshl_add_u64 v[202:203], v[202:203], 0, s[10:11]
	s_mov_b32 m0, s34
	ds_read_b128 v[186:189], v173 offset:49152
	ds_read_b128 v[190:193], v173 offset:50176
	ds_read_b128 v[194:197], v173 offset:51200
	ds_read_b128 v[198:201], v173 offset:52224
	ds_read_b128 v[206:209], v173 offset:53248
	ds_read_b128 v[210:213], v173 offset:54272
	ds_read_b128 v[214:217], v173 offset:55296
	ds_read_b128 v[218:221], v173 offset:56320
	global_load_lds_dwordx4 v[202:203], off
	s_add_i32 m0, s34, 0x2000
	s_add_u32 s26, s26, 0x40080
	v_lshl_add_u64 v[202:203], v[222:223], 0, s[10:11]
	s_addc_u32 s27, s27, 0
	s_add_i32 s34, s71, s44
	global_load_lds_dwordx4 v[202:203], off
	s_nop 0
	s_mov_b32 m0, s34
	s_nop 0
	global_load_lds_dwordx4 v146, s[26:27]
	s_nop 0
	s_add_i32 m0, s34, 0x2000
	s_nop 0
	global_load_lds_dwordx4 v150, s[26:27]
	v_lshl_add_u64 v[202:203], v[224:225], 0, s[10:11]
	s_mov_b32 m0, s57
	s_nop 0
	global_load_lds_dwordx4 v[202:203], off
	v_lshl_add_u64 v[202:203], v[226:227], 0, s[10:11]
	s_mov_b32 m0, s58
	s_nop 0
	global_load_lds_dwordx4 v[202:203], off
	s_waitcnt vmcnt(8)
	s_waitcnt lgkmcnt(0)
	s_barrier
	s_waitcnt lgkmcnt(0)
	v_mfma_f32_16x16x32_f16 v[60:63], v[104:107], v[186:189], v[60:63]
	v_mfma_f32_16x16x32_f16 v[56:59], v[112:115], v[186:189], v[56:59]
	v_mfma_f32_16x16x32_f16 v[44:47], v[104:107], v[194:197], v[44:47]
	v_mfma_f32_16x16x32_f16 v[40:43], v[112:115], v[194:197], v[40:43]
	v_mfma_f32_16x16x32_f16 v[28:31], v[104:107], v[206:209], v[28:31]
	v_mfma_f32_16x16x32_f16 v[24:27], v[112:115], v[206:209], v[24:27]
	v_mfma_f32_16x16x32_f16 v[12:15], v[104:107], v[214:217], v[12:15]
	v_mfma_f32_16x16x32_f16 v[8:11], v[112:115], v[214:217], v[8:11]
	v_mfma_f32_16x16x32_f16 v[60:63], v[108:111], v[190:193], v[60:63]
	v_mfma_f32_16x16x32_f16 v[56:59], v[116:119], v[190:193], v[56:59]
	v_mfma_f32_16x16x32_f16 v[44:47], v[108:111], v[198:201], v[44:47]
	v_mfma_f32_16x16x32_f16 v[40:43], v[116:119], v[198:201], v[40:43]
	v_mfma_f32_16x16x32_f16 v[28:31], v[108:111], v[210:213], v[28:31]
	v_mfma_f32_16x16x32_f16 v[24:27], v[116:119], v[210:213], v[24:27]
	v_mfma_f32_16x16x32_f16 v[12:15], v[108:111], v[218:221], v[12:15]
	v_mfma_f32_16x16x32_f16 v[8:11], v[116:119], v[218:221], v[8:11]
	v_mfma_f32_16x16x32_f16 v[52:55], v[160:163], v[186:189], v[52:55]
	v_mfma_f32_16x16x32_f16 v[48:51], v[178:181], v[186:189], v[48:51]
	v_mfma_f32_16x16x32_f16 v[36:39], v[160:163], v[194:197], v[36:39]
	v_mfma_f32_16x16x32_f16 v[32:35], v[178:181], v[194:197], v[32:35]
	v_mfma_f32_16x16x32_f16 v[20:23], v[160:163], v[206:209], v[20:23]
	v_mfma_f32_16x16x32_f16 v[16:19], v[178:181], v[206:209], v[16:19]
	v_mfma_f32_16x16x32_f16 v[4:7], v[160:163], v[214:217], v[4:7]
	v_mfma_f32_16x16x32_f16 v[0:3], v[178:181], v[214:217], v[0:3]
	v_mfma_f32_16x16x32_f16 v[52:55], v[164:167], v[190:193], v[52:55]
	v_mfma_f32_16x16x32_f16 v[48:51], v[182:185], v[190:193], v[48:51]
	v_mfma_f32_16x16x32_f16 v[36:39], v[164:167], v[198:201], v[36:39]
	v_mfma_f32_16x16x32_f16 v[32:35], v[182:185], v[198:201], v[32:35]
	v_mfma_f32_16x16x32_f16 v[20:23], v[164:167], v[210:213], v[20:23]
	v_mfma_f32_16x16x32_f16 v[16:19], v[182:185], v[210:213], v[16:19]
	v_mfma_f32_16x16x32_f16 v[4:7], v[164:167], v[218:221], v[4:7]
	v_mfma_f32_16x16x32_f16 v[0:3], v[182:185], v[218:221], v[0:3]
	s_barrier
	s_add_i32 s69, s69, 2
	s_add_u32 s24, s24, 0x100
	s_addc_u32 s25, s25, 0
	s_add_u32 s67, s67, 0x100
	s_addc_u32 s68, s68, 0
	s_cmp_gt_u32 s69, 13
.LBB0_220:
	ds_read_b128 v[104:107], v171
	ds_read_b128 v[108:111], v171 offset:1024
	ds_read_b128 v[112:115], v171 offset:2048
	ds_read_b128 v[116:119], v171 offset:3072
	ds_read_b128 v[160:163], v172
	ds_read_b128 v[164:167], v172 offset:1024
	ds_read_b128 v[178:181], v172 offset:2048
	ds_read_b128 v[182:185], v172 offset:3072
	s_add_u32 s26, s24, 0xfffc0080
	s_addc_u32 s27, s25, -1
	s_cmp_eq_u32 s69, 12
	s_cselect_b32 s35, s17, s27
	s_cselect_b32 s34, s65, s26
	s_cselect_b32 s27, s15, s68
	s_cselect_b32 s26, s66, s67
	s_nop 0
	s_add_i32 m0, s23, 0xc000
	ds_read_b128 v[186:189], v173
	ds_read_b128 v[190:193], v173 offset:1024
	ds_read_b128 v[194:197], v173 offset:2048
	ds_read_b128 v[198:201], v173 offset:3072
	ds_read_b128 v[206:209], v173 offset:4096
	ds_read_b128 v[210:213], v173 offset:5120
	ds_read_b128 v[214:217], v173 offset:6144
	ds_read_b128 v[218:221], v173 offset:7168
	global_load_lds_dwordx4 v152, s[24:25]
	s_nop 0
	s_add_i32 m0, s23, 0xe000
	s_nop 0
	global_load_lds_dwordx4 v154, s[24:25]
	s_waitcnt vmcnt(8)
	s_waitcnt lgkmcnt(0)
	s_barrier
	s_waitcnt lgkmcnt(0)
	v_mfma_f32_16x16x32_f16 v[140:143], v[104:107], v[186:189], v[140:143]
	v_mfma_f32_16x16x32_f16 v[136:139], v[112:115], v[186:189], v[136:139]
	v_mfma_f32_16x16x32_f16 v[124:127], v[104:107], v[194:197], v[124:127]
	v_mfma_f32_16x16x32_f16 v[120:123], v[112:115], v[194:197], v[120:123]
	v_mfma_f32_16x16x32_f16 v[92:95], v[104:107], v[206:209], v[92:95]
	v_mfma_f32_16x16x32_f16 v[88:91], v[112:115], v[206:209], v[88:91]
	v_mfma_f32_16x16x32_f16 v[76:79], v[104:107], v[214:217], v[76:79]
	v_mfma_f32_16x16x32_f16 v[72:75], v[112:115], v[214:217], v[72:75]
	v_mfma_f32_16x16x32_f16 v[140:143], v[108:111], v[190:193], v[140:143]
	v_mfma_f32_16x16x32_f16 v[136:139], v[116:119], v[190:193], v[136:139]
	v_mfma_f32_16x16x32_f16 v[124:127], v[108:111], v[198:201], v[124:127]
	v_mfma_f32_16x16x32_f16 v[120:123], v[116:119], v[198:201], v[120:123]
	v_mfma_f32_16x16x32_f16 v[92:95], v[108:111], v[210:213], v[92:95]
	v_mfma_f32_16x16x32_f16 v[88:91], v[116:119], v[210:213], v[88:91]
	v_mfma_f32_16x16x32_f16 v[76:79], v[108:111], v[218:221], v[76:79]
	v_mfma_f32_16x16x32_f16 v[72:75], v[116:119], v[218:221], v[72:75]
	v_mfma_f32_16x16x32_f16 v[132:135], v[160:163], v[186:189], v[132:135]
	v_mfma_f32_16x16x32_f16 v[128:131], v[178:181], v[186:189], v[128:131]
	v_mfma_f32_16x16x32_f16 v[100:103], v[160:163], v[194:197], v[100:103]
	v_mfma_f32_16x16x32_f16 v[96:99], v[178:181], v[194:197], v[96:99]
	v_mfma_f32_16x16x32_f16 v[84:87], v[160:163], v[206:209], v[84:87]
	v_mfma_f32_16x16x32_f16 v[80:83], v[178:181], v[206:209], v[80:83]
	v_mfma_f32_16x16x32_f16 v[68:71], v[160:163], v[214:217], v[68:71]
	v_mfma_f32_16x16x32_f16 v[64:67], v[178:181], v[214:217], v[64:67]
	v_mfma_f32_16x16x32_f16 v[132:135], v[164:167], v[190:193], v[132:135]
	v_mfma_f32_16x16x32_f16 v[128:131], v[182:185], v[190:193], v[128:131]
	v_mfma_f32_16x16x32_f16 v[100:103], v[164:167], v[198:201], v[100:103]
	v_mfma_f32_16x16x32_f16 v[96:99], v[182:185], v[198:201], v[96:99]
	v_mfma_f32_16x16x32_f16 v[84:87], v[164:167], v[210:213], v[84:87]
	v_mfma_f32_16x16x32_f16 v[80:83], v[182:185], v[210:213], v[80:83]
	v_mfma_f32_16x16x32_f16 v[68:71], v[164:167], v[218:221], v[68:71]
	v_mfma_f32_16x16x32_f16 v[64:67], v[182:185], v[218:221], v[64:67]
	s_barrier
	s_add_i32 s70, s60, s44
	v_lshl_add_u64 v[202:203], s[26:27], 0, v[146:147]
	s_mov_b32 m0, s70
	ds_read_b128 v[186:189], v173 offset:16384
	ds_read_b128 v[190:193], v173 offset:17408
	ds_read_b128 v[194:197], v173 offset:18432
	ds_read_b128 v[198:201], v173 offset:19456
	ds_read_b128 v[206:209], v173 offset:20480
	ds_read_b128 v[210:213], v173 offset:21504
	ds_read_b128 v[214:217], v173 offset:22528
	ds_read_b128 v[218:221], v173 offset:23552
	global_load_lds_dwordx4 v[202:203], off
	s_add_i32 m0, s70, 0x2000
	s_add_u32 s70, s26, 0x40000
	v_lshl_add_u64 v[222:223], s[26:27], 0, v[150:151]
	s_addc_u32 s71, s27, 0
	s_add_i32 s72, s61, s44
	global_load_lds_dwordx4 v[222:223], off
	s_nop 0
	s_mov_b32 m0, s72
	v_lshl_add_u64 v[226:227], s[34:35], 0, v[148:149]
	global_load_lds_dwordx4 v146, s[70:71]
	s_nop 0
	s_add_i32 m0, s72, 0x2000
	s_nop 0
	global_load_lds_dwordx4 v150, s[70:71]
	v_lshl_add_u64 v[224:225], s[34:35], 0, v[144:145]
	s_mov_b32 m0, s23
	s_nop 0
	global_load_lds_dwordx4 v[224:225], off
	s_mov_b32 m0, s45
	s_nop 0
	global_load_lds_dwordx4 v[226:227], off
	s_waitcnt vmcnt(8)
	s_waitcnt lgkmcnt(0)
	s_barrier
	s_waitcnt lgkmcnt(0)
	v_mfma_f32_16x16x32_f16 v[60:63], v[104:107], v[186:189], v[60:63]
	v_mfma_f32_16x16x32_f16 v[56:59], v[112:115], v[186:189], v[56:59]
	v_mfma_f32_16x16x32_f16 v[44:47], v[104:107], v[194:197], v[44:47]
	v_mfma_f32_16x16x32_f16 v[40:43], v[112:115], v[194:197], v[40:43]
	v_mfma_f32_16x16x32_f16 v[28:31], v[104:107], v[206:209], v[28:31]
	v_mfma_f32_16x16x32_f16 v[24:27], v[112:115], v[206:209], v[24:27]
	v_mfma_f32_16x16x32_f16 v[12:15], v[104:107], v[214:217], v[12:15]
	v_mfma_f32_16x16x32_f16 v[8:11], v[112:115], v[214:217], v[8:11]
	v_mfma_f32_16x16x32_f16 v[60:63], v[108:111], v[190:193], v[60:63]
	v_mfma_f32_16x16x32_f16 v[56:59], v[116:119], v[190:193], v[56:59]
	v_mfma_f32_16x16x32_f16 v[44:47], v[108:111], v[198:201], v[44:47]
	v_mfma_f32_16x16x32_f16 v[40:43], v[116:119], v[198:201], v[40:43]
	v_mfma_f32_16x16x32_f16 v[28:31], v[108:111], v[210:213], v[28:31]
	v_mfma_f32_16x16x32_f16 v[24:27], v[116:119], v[210:213], v[24:27]
	v_mfma_f32_16x16x32_f16 v[12:15], v[108:111], v[218:221], v[12:15]
	v_mfma_f32_16x16x32_f16 v[8:11], v[116:119], v[218:221], v[8:11]
	v_mfma_f32_16x16x32_f16 v[52:55], v[160:163], v[186:189], v[52:55]
	v_mfma_f32_16x16x32_f16 v[48:51], v[178:181], v[186:189], v[48:51]
	v_mfma_f32_16x16x32_f16 v[36:39], v[160:163], v[194:197], v[36:39]
	v_mfma_f32_16x16x32_f16 v[32:35], v[178:181], v[194:197], v[32:35]
	v_mfma_f32_16x16x32_f16 v[20:23], v[160:163], v[206:209], v[20:23]
	v_mfma_f32_16x16x32_f16 v[16:19], v[178:181], v[206:209], v[16:19]
	v_mfma_f32_16x16x32_f16 v[4:7], v[160:163], v[214:217], v[4:7]
	v_mfma_f32_16x16x32_f16 v[0:3], v[178:181], v[214:217], v[0:3]
	v_mfma_f32_16x16x32_f16 v[52:55], v[164:167], v[190:193], v[52:55]
	v_mfma_f32_16x16x32_f16 v[48:51], v[182:185], v[190:193], v[48:51]
	v_mfma_f32_16x16x32_f16 v[36:39], v[164:167], v[198:201], v[36:39]
	v_mfma_f32_16x16x32_f16 v[32:35], v[182:185], v[198:201], v[32:35]
	v_mfma_f32_16x16x32_f16 v[20:23], v[164:167], v[210:213], v[20:23]
	v_mfma_f32_16x16x32_f16 v[16:19], v[182:185], v[210:213], v[16:19]
	v_mfma_f32_16x16x32_f16 v[4:7], v[164:167], v[218:221], v[4:7]
	v_mfma_f32_16x16x32_f16 v[0:3], v[182:185], v[218:221], v[0:3]
	s_barrier
	s_add_i32 s70, 0, 0x18000
	s_add_i32 s71, 0, 0x1c000
	v_add_u32_e32 v116, s70, v169
	v_add_u32_e32 v177, s71, v169
	ds_read_b128 v[104:107], v116
	ds_read_b128 v[108:111], v116 offset:1024
	ds_read_b128 v[112:115], v116 offset:2048
	ds_read_b128 v[116:119], v116 offset:3072
	ds_read_b128 v[160:163], v177
	ds_read_b128 v[164:167], v177 offset:1024
	ds_read_b128 v[178:181], v177 offset:2048
	ds_read_b128 v[182:185], v177 offset:3072
	s_add_u32 s34, s34, 0x40000
	s_addc_u32 s35, s35, 0
	s_mov_b32 m0, s46
	s_nop 0
	ds_read_b128 v[186:189], v173 offset:32768
	ds_read_b128 v[190:193], v173 offset:33792
	ds_read_b128 v[194:197], v173 offset:34816
	ds_read_b128 v[198:201], v173 offset:35840
	ds_read_b128 v[206:209], v173 offset:36864
	ds_read_b128 v[210:213], v173 offset:37888
	ds_read_b128 v[214:217], v173 offset:38912
	ds_read_b128 v[218:221], v173 offset:39936
	global_load_lds_dwordx4 v144, s[34:35]
	s_nop 0
	s_mov_b32 m0, s47
	s_nop 0
	global_load_lds_dwordx4 v148, s[34:35]
	s_waitcnt vmcnt(8)
	s_waitcnt lgkmcnt(0)
	s_barrier
	s_waitcnt lgkmcnt(0)
	v_mfma_f32_16x16x32_f16 v[140:143], v[104:107], v[186:189], v[140:143]
	v_mfma_f32_16x16x32_f16 v[136:139], v[112:115], v[186:189], v[136:139]
	v_mfma_f32_16x16x32_f16 v[124:127], v[104:107], v[194:197], v[124:127]
	v_mfma_f32_16x16x32_f16 v[120:123], v[112:115], v[194:197], v[120:123]
	v_mfma_f32_16x16x32_f16 v[92:95], v[104:107], v[206:209], v[92:95]
	v_mfma_f32_16x16x32_f16 v[88:91], v[112:115], v[206:209], v[88:91]
	v_mfma_f32_16x16x32_f16 v[76:79], v[104:107], v[214:217], v[76:79]
	v_mfma_f32_16x16x32_f16 v[72:75], v[112:115], v[214:217], v[72:75]
	v_mfma_f32_16x16x32_f16 v[140:143], v[108:111], v[190:193], v[140:143]
	v_mfma_f32_16x16x32_f16 v[136:139], v[116:119], v[190:193], v[136:139]
	v_mfma_f32_16x16x32_f16 v[124:127], v[108:111], v[198:201], v[124:127]
	v_mfma_f32_16x16x32_f16 v[120:123], v[116:119], v[198:201], v[120:123]
	v_mfma_f32_16x16x32_f16 v[92:95], v[108:111], v[210:213], v[92:95]
	v_mfma_f32_16x16x32_f16 v[88:91], v[116:119], v[210:213], v[88:91]
	v_mfma_f32_16x16x32_f16 v[76:79], v[108:111], v[218:221], v[76:79]
	v_mfma_f32_16x16x32_f16 v[72:75], v[116:119], v[218:221], v[72:75]
	v_mfma_f32_16x16x32_f16 v[132:135], v[160:163], v[186:189], v[132:135]
	v_mfma_f32_16x16x32_f16 v[128:131], v[178:181], v[186:189], v[128:131]
	v_mfma_f32_16x16x32_f16 v[100:103], v[160:163], v[194:197], v[100:103]
	v_mfma_f32_16x16x32_f16 v[96:99], v[178:181], v[194:197], v[96:99]
	v_mfma_f32_16x16x32_f16 v[84:87], v[160:163], v[206:209], v[84:87]
	v_mfma_f32_16x16x32_f16 v[80:83], v[178:181], v[206:209], v[80:83]
	v_mfma_f32_16x16x32_f16 v[68:71], v[160:163], v[214:217], v[68:71]
	v_mfma_f32_16x16x32_f16 v[64:67], v[178:181], v[214:217], v[64:67]
	v_mfma_f32_16x16x32_f16 v[132:135], v[164:167], v[190:193], v[132:135]
	v_mfma_f32_16x16x32_f16 v[128:131], v[182:185], v[190:193], v[128:131]
	v_mfma_f32_16x16x32_f16 v[100:103], v[164:167], v[198:201], v[100:103]
	v_mfma_f32_16x16x32_f16 v[96:99], v[182:185], v[198:201], v[96:99]
	v_mfma_f32_16x16x32_f16 v[84:87], v[164:167], v[210:213], v[84:87]
	v_mfma_f32_16x16x32_f16 v[80:83], v[182:185], v[210:213], v[80:83]
	v_mfma_f32_16x16x32_f16 v[68:71], v[164:167], v[218:221], v[68:71]
	v_mfma_f32_16x16x32_f16 v[64:67], v[182:185], v[218:221], v[64:67]
	s_barrier
	s_add_i32 s34, s70, s44
	v_lshl_add_u64 v[202:203], v[202:203], 0, s[10:11]
	s_mov_b32 m0, s34
	ds_read_b128 v[186:189], v173 offset:49152
	ds_read_b128 v[190:193], v173 offset:50176
	ds_read_b128 v[194:197], v173 offset:51200
	ds_read_b128 v[198:201], v173 offset:52224
	ds_read_b128 v[206:209], v173 offset:53248
	ds_read_b128 v[210:213], v173 offset:54272
	ds_read_b128 v[214:217], v173 offset:55296
	ds_read_b128 v[218:221], v173 offset:56320
	global_load_lds_dwordx4 v[202:203], off
	s_add_i32 m0, s34, 0x2000
	s_add_u32 s26, s26, 0x40080
	v_lshl_add_u64 v[202:203], v[222:223], 0, s[10:11]
	s_addc_u32 s27, s27, 0
	s_add_i32 s34, s71, s44
	global_load_lds_dwordx4 v[202:203], off
	s_nop 0
	s_mov_b32 m0, s34
	s_nop 0
	global_load_lds_dwordx4 v146, s[26:27]
	s_nop 0
	s_add_i32 m0, s34, 0x2000
	s_nop 0
	global_load_lds_dwordx4 v150, s[26:27]
	v_lshl_add_u64 v[202:203], v[224:225], 0, s[10:11]
	s_mov_b32 m0, s57
	s_nop 0
	global_load_lds_dwordx4 v[202:203], off
	v_lshl_add_u64 v[202:203], v[226:227], 0, s[10:11]
	s_mov_b32 m0, s58
	s_nop 0
	global_load_lds_dwordx4 v[202:203], off
	s_waitcnt vmcnt(8)
	s_waitcnt lgkmcnt(0)
	s_barrier
	s_waitcnt lgkmcnt(0)
	v_mfma_f32_16x16x32_f16 v[60:63], v[104:107], v[186:189], v[60:63]
	v_mfma_f32_16x16x32_f16 v[56:59], v[112:115], v[186:189], v[56:59]
	v_mfma_f32_16x16x32_f16 v[44:47], v[104:107], v[194:197], v[44:47]
	v_mfma_f32_16x16x32_f16 v[40:43], v[112:115], v[194:197], v[40:43]
	v_mfma_f32_16x16x32_f16 v[28:31], v[104:107], v[206:209], v[28:31]
	v_mfma_f32_16x16x32_f16 v[24:27], v[112:115], v[206:209], v[24:27]
	v_mfma_f32_16x16x32_f16 v[12:15], v[104:107], v[214:217], v[12:15]
	v_mfma_f32_16x16x32_f16 v[8:11], v[112:115], v[214:217], v[8:11]
	v_mfma_f32_16x16x32_f16 v[60:63], v[108:111], v[190:193], v[60:63]
	v_mfma_f32_16x16x32_f16 v[56:59], v[116:119], v[190:193], v[56:59]
	v_mfma_f32_16x16x32_f16 v[44:47], v[108:111], v[198:201], v[44:47]
	v_mfma_f32_16x16x32_f16 v[40:43], v[116:119], v[198:201], v[40:43]
	v_mfma_f32_16x16x32_f16 v[28:31], v[108:111], v[210:213], v[28:31]
	v_mfma_f32_16x16x32_f16 v[24:27], v[116:119], v[210:213], v[24:27]
	v_mfma_f32_16x16x32_f16 v[12:15], v[108:111], v[218:221], v[12:15]
	v_mfma_f32_16x16x32_f16 v[8:11], v[116:119], v[218:221], v[8:11]
	v_mfma_f32_16x16x32_f16 v[52:55], v[160:163], v[186:189], v[52:55]
	v_mfma_f32_16x16x32_f16 v[48:51], v[178:181], v[186:189], v[48:51]
	v_mfma_f32_16x16x32_f16 v[36:39], v[160:163], v[194:197], v[36:39]
	v_mfma_f32_16x16x32_f16 v[32:35], v[178:181], v[194:197], v[32:35]
	v_mfma_f32_16x16x32_f16 v[20:23], v[160:163], v[206:209], v[20:23]
	v_mfma_f32_16x16x32_f16 v[16:19], v[178:181], v[206:209], v[16:19]
	v_mfma_f32_16x16x32_f16 v[4:7], v[160:163], v[214:217], v[4:7]
	v_mfma_f32_16x16x32_f16 v[0:3], v[178:181], v[214:217], v[0:3]
	v_mfma_f32_16x16x32_f16 v[52:55], v[164:167], v[190:193], v[52:55]
	v_mfma_f32_16x16x32_f16 v[48:51], v[182:185], v[190:193], v[48:51]
	v_mfma_f32_16x16x32_f16 v[36:39], v[164:167], v[198:201], v[36:39]
	v_mfma_f32_16x16x32_f16 v[32:35], v[182:185], v[198:201], v[32:35]
	v_mfma_f32_16x16x32_f16 v[20:23], v[164:167], v[210:213], v[20:23]
	v_mfma_f32_16x16x32_f16 v[16:19], v[182:185], v[210:213], v[16:19]
	v_mfma_f32_16x16x32_f16 v[4:7], v[164:167], v[218:221], v[4:7]
	v_mfma_f32_16x16x32_f16 v[0:3], v[182:185], v[218:221], v[0:3]
	s_barrier
	s_add_i32 s69, s69, 2
	s_add_u32 s24, s24, 0x100
	s_addc_u32 s25, s25, 0
	s_add_u32 s67, s67, 0x100
	s_addc_u32 s68, s68, 0
	s_cmp_gt_u32 s69, 13
	s_cbranch_scc0 .LBB0_220
	s_and_b64 vcc, exec, s[12:13]
	s_cbranch_vccz .LBB0_223
	s_barrier

.LBB0_872:
	s_ashr_i32 s17, s16, 31
	s_lshl_b64 s[18:19], s[16:17], 19
	s_add_u32 s18, s42, s18
	s_addc_u32 s19, s43, s19
	s_and_b64 s[20:21], s[2:3], exec
	s_cselect_b32 s17, s19, s25
	s_cselect_b32 s63, s18, s24
	s_ashr_i32 s15, s14, 31
	s_lshl_b64 s[20:21], s[14:15], 19
	s_add_u32 s20, s40, s20
	s_addc_u32 s21, s41, s21
	s_and_b64 s[34:35], s[2:3], exec
	s_cselect_b32 s15, s21, s27
	s_cselect_b32 s64, s20, s26
	s_add_u32 s24, s24, 0x40080
	s_addc_u32 s25, s25, 0
	s_add_u32 s65, s26, 0x100
	s_addc_u32 s66, s27, 0
	s_mov_b32 s67, -2
	ds_read_b128 v[104:107], v171
	ds_read_b128 v[108:111], v171 offset:1024
	ds_read_b128 v[112:115], v171 offset:2048
	ds_read_b128 v[116:119], v171 offset:3072
	ds_read_b128 v[160:163], v172
	ds_read_b128 v[164:167], v172 offset:1024
	ds_read_b128 v[178:181], v172 offset:2048
	ds_read_b128 v[182:185], v172 offset:3072
	s_add_u32 s26, s24, 0xfffc0080
	s_addc_u32 s27, s25, -1
	s_cmp_eq_u32 s67, 12
	s_cselect_b32 s35, s17, s27
	s_cselect_b32 s34, s63, s26
	s_cselect_b32 s27, s15, s66
	s_cselect_b32 s26, s64, s65
	v_lshl_add_u64 v[202:203], s[24:25], 0, v[152:153]
	s_add_i32 m0, s23, 0xc000
	ds_read_b128 v[186:189], v173
	ds_read_b128 v[190:193], v173 offset:1024
	ds_read_b128 v[194:197], v173 offset:2048
	ds_read_b128 v[198:201], v173 offset:3072
	ds_read_b128 v[206:209], v173 offset:4096
	ds_read_b128 v[210:213], v173 offset:5120
	ds_read_b128 v[214:217], v173 offset:6144
	ds_read_b128 v[218:221], v173 offset:7168
	global_load_lds_dwordx4 v[202:203], off
	v_lshl_add_u64 v[202:203], s[24:25], 0, v[154:155]
	s_add_i32 m0, s23, 0xe000
	s_nop 0
	global_load_lds_dwordx4 v[202:203], off
	s_waitcnt vmcnt(8)
	s_waitcnt lgkmcnt(0)
	s_barrier
	s_waitcnt lgkmcnt(0)
	v_mfma_f32_16x16x32_f16 v[140:143], v[104:107], v[186:189], 0
	v_mfma_f32_16x16x32_f16 v[136:139], v[112:115], v[186:189], 0
	v_mfma_f32_16x16x32_f16 v[124:127], v[104:107], v[194:197], 0
	v_mfma_f32_16x16x32_f16 v[120:123], v[112:115], v[194:197], 0
	v_mfma_f32_16x16x32_f16 v[92:95], v[104:107], v[206:209], 0
	v_mfma_f32_16x16x32_f16 v[88:91], v[112:115], v[206:209], 0
	v_mfma_f32_16x16x32_f16 v[76:79], v[104:107], v[214:217], 0
	v_mfma_f32_16x16x32_f16 v[72:75], v[112:115], v[214:217], 0
	v_mfma_f32_16x16x32_f16 v[140:143], v[108:111], v[190:193], v[140:143]
	v_mfma_f32_16x16x32_f16 v[136:139], v[116:119], v[190:193], v[136:139]
	v_mfma_f32_16x16x32_f16 v[124:127], v[108:111], v[198:201], v[124:127]
	v_mfma_f32_16x16x32_f16 v[120:123], v[116:119], v[198:201], v[120:123]
	v_mfma_f32_16x16x32_f16 v[92:95], v[108:111], v[210:213], v[92:95]
	v_mfma_f32_16x16x32_f16 v[88:91], v[116:119], v[210:213], v[88:91]
	v_mfma_f32_16x16x32_f16 v[76:79], v[108:111], v[218:221], v[76:79]
	v_mfma_f32_16x16x32_f16 v[72:75], v[116:119], v[218:221], v[72:75]
	v_mfma_f32_16x16x32_f16 v[132:135], v[160:163], v[186:189], 0
	v_mfma_f32_16x16x32_f16 v[128:131], v[178:181], v[186:189], 0
	v_mfma_f32_16x16x32_f16 v[100:103], v[160:163], v[194:197], 0
	v_mfma_f32_16x16x32_f16 v[96:99], v[178:181], v[194:197], 0
	v_mfma_f32_16x16x32_f16 v[84:87], v[160:163], v[206:209], 0
	v_mfma_f32_16x16x32_f16 v[80:83], v[178:181], v[206:209], 0
	v_mfma_f32_16x16x32_f16 v[68:71], v[160:163], v[214:217], 0
	v_mfma_f32_16x16x32_f16 v[64:67], v[178:181], v[214:217], 0
	v_mfma_f32_16x16x32_f16 v[132:135], v[164:167], v[190:193], v[132:135]
	v_mfma_f32_16x16x32_f16 v[128:131], v[182:185], v[190:193], v[128:131]
	v_mfma_f32_16x16x32_f16 v[100:103], v[164:167], v[198:201], v[100:103]
	v_mfma_f32_16x16x32_f16 v[96:99], v[182:185], v[198:201], v[96:99]
	v_mfma_f32_16x16x32_f16 v[84:87], v[164:167], v[210:213], v[84:87]
	v_mfma_f32_16x16x32_f16 v[80:83], v[182:185], v[210:213], v[80:83]
	v_mfma_f32_16x16x32_f16 v[68:71], v[164:167], v[218:221], v[68:71]
	v_mfma_f32_16x16x32_f16 v[64:67], v[182:185], v[218:221], v[64:67]
	s_barrier
	s_add_i32 s68, s58, s44
	v_lshl_add_u64 v[202:203], s[26:27], 0, v[146:147]
	s_mov_b32 m0, s68
	ds_read_b128 v[186:189], v173 offset:16384
	ds_read_b128 v[190:193], v173 offset:17408
	ds_read_b128 v[194:197], v173 offset:18432
	ds_read_b128 v[198:201], v173 offset:19456
	ds_read_b128 v[206:209], v173 offset:20480
	ds_read_b128 v[210:213], v173 offset:21504
	ds_read_b128 v[214:217], v173 offset:22528
	ds_read_b128 v[218:221], v173 offset:23552
	global_load_lds_dwordx4 v[202:203], off
	s_add_i32 m0, s68, 0x2000
	s_add_u32 s68, s26, 0x40000
	v_lshl_add_u64 v[222:223], s[26:27], 0, v[150:151]
	s_addc_u32 s69, s27, 0
	s_add_i32 s70, s59, s44
	global_load_lds_dwordx4 v[222:223], off
	v_lshl_add_u64 v[224:225], s[68:69], 0, v[146:147]
	s_mov_b32 m0, s70
	v_lshl_add_u64 v[226:227], s[34:35], 0, v[148:149]
	global_load_lds_dwordx4 v[224:225], off
	v_lshl_add_u64 v[224:225], s[68:69], 0, v[150:151]
	s_add_i32 m0, s70, 0x2000
	s_nop 0
	global_load_lds_dwordx4 v[224:225], off
	v_lshl_add_u64 v[224:225], s[34:35], 0, v[144:145]
	s_mov_b32 m0, s23
	s_nop 0
	global_load_lds_dwordx4 v[224:225], off
	s_mov_b32 m0, s45
	s_nop 0
	global_load_lds_dwordx4 v[226:227], off
	s_waitcnt vmcnt(8)
	s_waitcnt lgkmcnt(0)
	s_barrier
	s_waitcnt lgkmcnt(0)
	v_mfma_f32_16x16x32_f16 v[60:63], v[104:107], v[186:189], 0
	v_mfma_f32_16x16x32_f16 v[56:59], v[112:115], v[186:189], 0
	v_mfma_f32_16x16x32_f16 v[44:47], v[104:107], v[194:197], 0
	v_mfma_f32_16x16x32_f16 v[40:43], v[112:115], v[194:197], 0
	v_mfma_f32_16x16x32_f16 v[28:31], v[104:107], v[206:209], 0
	v_mfma_f32_16x16x32_f16 v[24:27], v[112:115], v[206:209], 0
	v_mfma_f32_16x16x32_f16 v[12:15], v[104:107], v[214:217], 0
	v_mfma_f32_16x16x32_f16 v[8:11], v[112:115], v[214:217], 0
	v_mfma_f32_16x16x32_f16 v[60:63], v[108:111], v[190:193], v[60:63]
	v_mfma_f32_16x16x32_f16 v[56:59], v[116:119], v[190:193], v[56:59]
	v_mfma_f32_16x16x32_f16 v[44:47], v[108:111], v[198:201], v[44:47]
	v_mfma_f32_16x16x32_f16 v[40:43], v[116:119], v[198:201], v[40:43]
	v_mfma_f32_16x16x32_f16 v[28:31], v[108:111], v[210:213], v[28:31]
	v_mfma_f32_16x16x32_f16 v[24:27], v[116:119], v[210:213], v[24:27]
	v_mfma_f32_16x16x32_f16 v[12:15], v[108:111], v[218:221], v[12:15]
	v_mfma_f32_16x16x32_f16 v[8:11], v[116:119], v[218:221], v[8:11]
	v_mfma_f32_16x16x32_f16 v[52:55], v[160:163], v[186:189], 0
	v_mfma_f32_16x16x32_f16 v[48:51], v[178:181], v[186:189], 0
	v_mfma_f32_16x16x32_f16 v[36:39], v[160:163], v[194:197], 0
	v_mfma_f32_16x16x32_f16 v[32:35], v[178:181], v[194:197], 0
	v_mfma_f32_16x16x32_f16 v[20:23], v[160:163], v[206:209], 0
	v_mfma_f32_16x16x32_f16 v[16:19], v[178:181], v[206:209], 0
	v_mfma_f32_16x16x32_f16 v[4:7], v[160:163], v[214:217], 0
	v_mfma_f32_16x16x32_f16 v[0:3], v[178:181], v[214:217], 0
	v_mfma_f32_16x16x32_f16 v[52:55], v[164:167], v[190:193], v[52:55]
	v_mfma_f32_16x16x32_f16 v[48:51], v[182:185], v[190:193], v[48:51]
	v_mfma_f32_16x16x32_f16 v[36:39], v[164:167], v[198:201], v[36:39]
	v_mfma_f32_16x16x32_f16 v[32:35], v[182:185], v[198:201], v[32:35]
	v_mfma_f32_16x16x32_f16 v[20:23], v[164:167], v[210:213], v[20:23]
	v_mfma_f32_16x16x32_f16 v[16:19], v[182:185], v[210:213], v[16:19]
	v_mfma_f32_16x16x32_f16 v[4:7], v[164:167], v[218:221], v[4:7]
	v_mfma_f32_16x16x32_f16 v[0:3], v[182:185], v[218:221], v[0:3]
	s_barrier
	s_add_i32 s68, 0, 0x18000
	s_add_i32 s69, 0, 0x1c000
	v_add_u32_e32 v116, s68, v169
	v_add_u32_e32 v177, s69, v169
	ds_read_b128 v[104:107], v116
	ds_read_b128 v[108:111], v116 offset:1024
	ds_read_b128 v[112:115], v116 offset:2048
	ds_read_b128 v[116:119], v116 offset:3072
	ds_read_b128 v[160:163], v177
	ds_read_b128 v[164:167], v177 offset:1024
	ds_read_b128 v[178:181], v177 offset:2048
	ds_read_b128 v[182:185], v177 offset:3072
	s_add_u32 s34, s34, 0x40000
	s_addc_u32 s35, s35, 0
	s_mov_b32 m0, s46
	v_lshl_add_u64 v[228:229], s[34:35], 0, v[144:145]
	ds_read_b128 v[186:189], v173 offset:32768
	ds_read_b128 v[190:193], v173 offset:33792
	ds_read_b128 v[194:197], v173 offset:34816
	ds_read_b128 v[198:201], v173 offset:35840
	ds_read_b128 v[206:209], v173 offset:36864
	ds_read_b128 v[210:213], v173 offset:37888
	ds_read_b128 v[214:217], v173 offset:38912
	ds_read_b128 v[218:221], v173 offset:39936
	global_load_lds_dwordx4 v[228:229], off
	v_lshl_add_u64 v[228:229], s[34:35], 0, v[148:149]
	s_mov_b32 m0, s47
	s_nop 0
	global_load_lds_dwordx4 v[228:229], off
	s_waitcnt vmcnt(8)
	s_waitcnt lgkmcnt(0)
	s_barrier
	s_waitcnt lgkmcnt(0)
	v_mfma_f32_16x16x32_f16 v[140:143], v[104:107], v[186:189], v[140:143]
	v_mfma_f32_16x16x32_f16 v[136:139], v[112:115], v[186:189], v[136:139]
	v_mfma_f32_16x16x32_f16 v[124:127], v[104:107], v[194:197], v[124:127]
	v_mfma_f32_16x16x32_f16 v[120:123], v[112:115], v[194:197], v[120:123]
	v_mfma_f32_16x16x32_f16 v[92:95], v[104:107], v[206:209], v[92:95]
	v_mfma_f32_16x16x32_f16 v[88:91], v[112:115], v[206:209], v[88:91]
	v_mfma_f32_16x16x32_f16 v[76:79], v[104:107], v[214:217], v[76:79]
	v_mfma_f32_16x16x32_f16 v[72:75], v[112:115], v[214:217], v[72:75]
	v_mfma_f32_16x16x32_f16 v[140:143], v[108:111], v[190:193], v[140:143]
	v_mfma_f32_16x16x32_f16 v[136:139], v[116:119], v[190:193], v[136:139]
	v_mfma_f32_16x16x32_f16 v[124:127], v[108:111], v[198:201], v[124:127]
	v_mfma_f32_16x16x32_f16 v[120:123], v[116:119], v[198:201], v[120:123]
	v_mfma_f32_16x16x32_f16 v[92:95], v[108:111], v[210:213], v[92:95]
	v_mfma_f32_16x16x32_f16 v[88:91], v[116:119], v[210:213], v[88:91]
	v_mfma_f32_16x16x32_f16 v[76:79], v[108:111], v[218:221], v[76:79]
	v_mfma_f32_16x16x32_f16 v[72:75], v[116:119], v[218:221], v[72:75]
	v_mfma_f32_16x16x32_f16 v[132:135], v[160:163], v[186:189], v[132:135]
	v_mfma_f32_16x16x32_f16 v[128:131], v[178:181], v[186:189], v[128:131]
	v_mfma_f32_16x16x32_f16 v[100:103], v[160:163], v[194:197], v[100:103]
	v_mfma_f32_16x16x32_f16 v[96:99], v[178:181], v[194:197], v[96:99]
	v_mfma_f32_16x16x32_f16 v[84:87], v[160:163], v[206:209], v[84:87]
	v_mfma_f32_16x16x32_f16 v[80:83], v[178:181], v[206:209], v[80:83]
	v_mfma_f32_16x16x32_f16 v[68:71], v[160:163], v[214:217], v[68:71]
	v_mfma_f32_16x16x32_f16 v[64:67], v[178:181], v[214:217], v[64:67]
	v_mfma_f32_16x16x32_f16 v[132:135], v[164:167], v[190:193], v[132:135]
	v_mfma_f32_16x16x32_f16 v[128:131], v[182:185], v[190:193], v[128:131]
	v_mfma_f32_16x16x32_f16 v[100:103], v[164:167], v[198:201], v[100:103]
	v_mfma_f32_16x16x32_f16 v[96:99], v[182:185], v[198:201], v[96:99]
	v_mfma_f32_16x16x32_f16 v[84:87], v[164:167], v[210:213], v[84:87]
	v_mfma_f32_16x16x32_f16 v[80:83], v[182:185], v[210:213], v[80:83]
	v_mfma_f32_16x16x32_f16 v[68:71], v[164:167], v[218:221], v[68:71]
	v_mfma_f32_16x16x32_f16 v[64:67], v[182:185], v[218:221], v[64:67]
	s_barrier
	s_add_i32 s34, s68, s44
	v_lshl_add_u64 v[202:203], v[202:203], 0, s[10:11]
	s_mov_b32 m0, s34
	ds_read_b128 v[186:189], v173 offset:49152
	ds_read_b128 v[190:193], v173 offset:50176
	ds_read_b128 v[194:197], v173 offset:51200
	ds_read_b128 v[198:201], v173 offset:52224
	ds_read_b128 v[206:209], v173 offset:53248
	ds_read_b128 v[210:213], v173 offset:54272
	ds_read_b128 v[214:217], v173 offset:55296
	ds_read_b128 v[218:221], v173 offset:56320
	global_load_lds_dwordx4 v[202:203], off
	s_add_i32 m0, s34, 0x2000
	s_add_u32 s26, s26, 0x40080
	v_lshl_add_u64 v[202:203], v[222:223], 0, s[10:11]
	s_addc_u32 s27, s27, 0
	s_add_i32 s34, s69, s44
	global_load_lds_dwordx4 v[202:203], off
	s_nop 0
	s_mov_b32 m0, s34
	s_nop 0
	global_load_lds_dwordx4 v146, s[26:27]
	s_nop 0
	s_add_i32 m0, s34, 0x2000
	s_nop 0
	global_load_lds_dwordx4 v150, s[26:27]
	v_lshl_add_u64 v[202:203], v[224:225], 0, s[10:11]
	s_mov_b32 m0, s55
	s_nop 0
	global_load_lds_dwordx4 v[202:203], off
	v_lshl_add_u64 v[202:203], v[226:227], 0, s[10:11]
	s_mov_b32 m0, s56
	s_nop 0
	global_load_lds_dwordx4 v[202:203], off
	s_waitcnt vmcnt(8)
	s_waitcnt lgkmcnt(0)
	s_barrier
	s_waitcnt lgkmcnt(0)
	v_mfma_f32_16x16x32_f16 v[60:63], v[104:107], v[186:189], v[60:63]
	v_mfma_f32_16x16x32_f16 v[56:59], v[112:115], v[186:189], v[56:59]
	v_mfma_f32_16x16x32_f16 v[44:47], v[104:107], v[194:197], v[44:47]
	v_mfma_f32_16x16x32_f16 v[40:43], v[112:115], v[194:197], v[40:43]
	v_mfma_f32_16x16x32_f16 v[28:31], v[104:107], v[206:209], v[28:31]
	v_mfma_f32_16x16x32_f16 v[24:27], v[112:115], v[206:209], v[24:27]
	v_mfma_f32_16x16x32_f16 v[12:15], v[104:107], v[214:217], v[12:15]
	v_mfma_f32_16x16x32_f16 v[8:11], v[112:115], v[214:217], v[8:11]
	v_mfma_f32_16x16x32_f16 v[60:63], v[108:111], v[190:193], v[60:63]
	v_mfma_f32_16x16x32_f16 v[56:59], v[116:119], v[190:193], v[56:59]
	v_mfma_f32_16x16x32_f16 v[44:47], v[108:111], v[198:201], v[44:47]
	v_mfma_f32_16x16x32_f16 v[40:43], v[116:119], v[198:201], v[40:43]
	v_mfma_f32_16x16x32_f16 v[28:31], v[108:111], v[210:213], v[28:31]
	v_mfma_f32_16x16x32_f16 v[24:27], v[116:119], v[210:213], v[24:27]
	v_mfma_f32_16x16x32_f16 v[12:15], v[108:111], v[218:221], v[12:15]
	v_mfma_f32_16x16x32_f16 v[8:11], v[116:119], v[218:221], v[8:11]
	v_mfma_f32_16x16x32_f16 v[52:55], v[160:163], v[186:189], v[52:55]
	v_mfma_f32_16x16x32_f16 v[48:51], v[178:181], v[186:189], v[48:51]
	v_mfma_f32_16x16x32_f16 v[36:39], v[160:163], v[194:197], v[36:39]
	v_mfma_f32_16x16x32_f16 v[32:35], v[178:181], v[194:197], v[32:35]
	v_mfma_f32_16x16x32_f16 v[20:23], v[160:163], v[206:209], v[20:23]
	v_mfma_f32_16x16x32_f16 v[16:19], v[178:181], v[206:209], v[16:19]
	v_mfma_f32_16x16x32_f16 v[4:7], v[160:163], v[214:217], v[4:7]
	v_mfma_f32_16x16x32_f16 v[0:3], v[178:181], v[214:217], v[0:3]
	v_mfma_f32_16x16x32_f16 v[52:55], v[164:167], v[190:193], v[52:55]
	v_mfma_f32_16x16x32_f16 v[48:51], v[182:185], v[190:193], v[48:51]
	v_mfma_f32_16x16x32_f16 v[36:39], v[164:167], v[198:201], v[36:39]
	v_mfma_f32_16x16x32_f16 v[32:35], v[182:185], v[198:201], v[32:35]
	v_mfma_f32_16x16x32_f16 v[20:23], v[164:167], v[210:213], v[20:23]
	v_mfma_f32_16x16x32_f16 v[16:19], v[182:185], v[210:213], v[16:19]
	v_mfma_f32_16x16x32_f16 v[4:7], v[164:167], v[218:221], v[4:7]
	v_mfma_f32_16x16x32_f16 v[0:3], v[182:185], v[218:221], v[0:3]
	s_barrier
	s_add_i32 s67, s67, 2
	s_add_u32 s24, s24, 0x100
	s_addc_u32 s25, s25, 0
	s_add_u32 s65, s65, 0x100
	s_addc_u32 s66, s66, 0
	s_cmp_gt_u32 s67, 13
.LBB0_873:
	ds_read_b128 v[104:107], v171
	ds_read_b128 v[108:111], v171 offset:1024
	ds_read_b128 v[112:115], v171 offset:2048
	ds_read_b128 v[116:119], v171 offset:3072
	ds_read_b128 v[160:163], v172
	ds_read_b128 v[164:167], v172 offset:1024
	ds_read_b128 v[178:181], v172 offset:2048
	ds_read_b128 v[182:185], v172 offset:3072
	s_add_u32 s26, s24, 0xfffc0080
	s_addc_u32 s27, s25, -1
	s_cmp_eq_u32 s67, 12
	s_cselect_b32 s35, s17, s27
	s_cselect_b32 s34, s63, s26
	s_cselect_b32 s27, s15, s66
	s_cselect_b32 s26, s64, s65
	s_nop 0
	s_add_i32 m0, s23, 0xc000
	ds_read_b128 v[186:189], v173
	ds_read_b128 v[190:193], v173 offset:1024
	ds_read_b128 v[194:197], v173 offset:2048
	ds_read_b128 v[198:201], v173 offset:3072
	ds_read_b128 v[206:209], v173 offset:4096
	ds_read_b128 v[210:213], v173 offset:5120
	ds_read_b128 v[214:217], v173 offset:6144
	ds_read_b128 v[218:221], v173 offset:7168
	global_load_lds_dwordx4 v152, s[24:25]
	s_nop 0
	s_add_i32 m0, s23, 0xe000
	s_nop 0
	global_load_lds_dwordx4 v154, s[24:25]
	s_waitcnt vmcnt(8)
	s_waitcnt lgkmcnt(0)
	s_barrier
	s_waitcnt lgkmcnt(0)
	v_mfma_f32_16x16x32_f16 v[140:143], v[104:107], v[186:189], v[140:143]
	v_mfma_f32_16x16x32_f16 v[136:139], v[112:115], v[186:189], v[136:139]
	v_mfma_f32_16x16x32_f16 v[124:127], v[104:107], v[194:197], v[124:127]
	v_mfma_f32_16x16x32_f16 v[120:123], v[112:115], v[194:197], v[120:123]
	v_mfma_f32_16x16x32_f16 v[92:95], v[104:107], v[206:209], v[92:95]
	v_mfma_f32_16x16x32_f16 v[88:91], v[112:115], v[206:209], v[88:91]
	v_mfma_f32_16x16x32_f16 v[76:79], v[104:107], v[214:217], v[76:79]
	v_mfma_f32_16x16x32_f16 v[72:75], v[112:115], v[214:217], v[72:75]
	v_mfma_f32_16x16x32_f16 v[140:143], v[108:111], v[190:193], v[140:143]
	v_mfma_f32_16x16x32_f16 v[136:139], v[116:119], v[190:193], v[136:139]
	v_mfma_f32_16x16x32_f16 v[124:127], v[108:111], v[198:201], v[124:127]
	v_mfma_f32_16x16x32_f16 v[120:123], v[116:119], v[198:201], v[120:123]
	v_mfma_f32_16x16x32_f16 v[92:95], v[108:111], v[210:213], v[92:95]
	v_mfma_f32_16x16x32_f16 v[88:91], v[116:119], v[210:213], v[88:91]
	v_mfma_f32_16x16x32_f16 v[76:79], v[108:111], v[218:221], v[76:79]
	v_mfma_f32_16x16x32_f16 v[72:75], v[116:119], v[218:221], v[72:75]
	v_mfma_f32_16x16x32_f16 v[132:135], v[160:163], v[186:189], v[132:135]
	v_mfma_f32_16x16x32_f16 v[128:131], v[178:181], v[186:189], v[128:131]
	v_mfma_f32_16x16x32_f16 v[100:103], v[160:163], v[194:197], v[100:103]
	v_mfma_f32_16x16x32_f16 v[96:99], v[178:181], v[194:197], v[96:99]
	v_mfma_f32_16x16x32_f16 v[84:87], v[160:163], v[206:209], v[84:87]
	v_mfma_f32_16x16x32_f16 v[80:83], v[178:181], v[206:209], v[80:83]
	v_mfma_f32_16x16x32_f16 v[68:71], v[160:163], v[214:217], v[68:71]
	v_mfma_f32_16x16x32_f16 v[64:67], v[178:181], v[214:217], v[64:67]
	v_mfma_f32_16x16x32_f16 v[132:135], v[164:167], v[190:193], v[132:135]
	v_mfma_f32_16x16x32_f16 v[128:131], v[182:185], v[190:193], v[128:131]
	v_mfma_f32_16x16x32_f16 v[100:103], v[164:167], v[198:201], v[100:103]
	v_mfma_f32_16x16x32_f16 v[96:99], v[182:185], v[198:201], v[96:99]
	v_mfma_f32_16x16x32_f16 v[84:87], v[164:167], v[210:213], v[84:87]
	v_mfma_f32_16x16x32_f16 v[80:83], v[182:185], v[210:213], v[80:83]
	v_mfma_f32_16x16x32_f16 v[68:71], v[164:167], v[218:221], v[68:71]
	v_mfma_f32_16x16x32_f16 v[64:67], v[182:185], v[218:221], v[64:67]
	s_barrier
	s_add_i32 s68, s58, s44
	v_lshl_add_u64 v[202:203], s[26:27], 0, v[146:147]
	s_mov_b32 m0, s68
	ds_read_b128 v[186:189], v173 offset:16384
	ds_read_b128 v[190:193], v173 offset:17408
	ds_read_b128 v[194:197], v173 offset:18432
	ds_read_b128 v[198:201], v173 offset:19456
	ds_read_b128 v[206:209], v173 offset:20480
	ds_read_b128 v[210:213], v173 offset:21504
	ds_read_b128 v[214:217], v173 offset:22528
	ds_read_b128 v[218:221], v173 offset:23552
	global_load_lds_dwordx4 v[202:203], off
	s_add_i32 m0, s68, 0x2000
	s_add_u32 s68, s26, 0x40000
	v_lshl_add_u64 v[222:223], s[26:27], 0, v[150:151]
	s_addc_u32 s69, s27, 0
	s_add_i32 s70, s59, s44
	global_load_lds_dwordx4 v[222:223], off
	s_nop 0
	s_mov_b32 m0, s70
	v_lshl_add_u64 v[226:227], s[34:35], 0, v[148:149]
	global_load_lds_dwordx4 v146, s[68:69]
	s_nop 0
	s_add_i32 m0, s70, 0x2000
	s_nop 0
	global_load_lds_dwordx4 v150, s[68:69]
	v_lshl_add_u64 v[224:225], s[34:35], 0, v[144:145]
	s_mov_b32 m0, s23
	s_nop 0
	global_load_lds_dwordx4 v[224:225], off
	s_mov_b32 m0, s45
	s_nop 0
	global_load_lds_dwordx4 v[226:227], off
	s_waitcnt vmcnt(8)
	s_waitcnt lgkmcnt(0)
	s_barrier
	s_waitcnt lgkmcnt(0)
	v_mfma_f32_16x16x32_f16 v[60:63], v[104:107], v[186:189], v[60:63]
	v_mfma_f32_16x16x32_f16 v[56:59], v[112:115], v[186:189], v[56:59]
	v_mfma_f32_16x16x32_f16 v[44:47], v[104:107], v[194:197], v[44:47]
	v_mfma_f32_16x16x32_f16 v[40:43], v[112:115], v[194:197], v[40:43]
	v_mfma_f32_16x16x32_f16 v[28:31], v[104:107], v[206:209], v[28:31]
	v_mfma_f32_16x16x32_f16 v[24:27], v[112:115], v[206:209], v[24:27]
	v_mfma_f32_16x16x32_f16 v[12:15], v[104:107], v[214:217], v[12:15]
	v_mfma_f32_16x16x32_f16 v[8:11], v[112:115], v[214:217], v[8:11]
	v_mfma_f32_16x16x32_f16 v[60:63], v[108:111], v[190:193], v[60:63]
	v_mfma_f32_16x16x32_f16 v[56:59], v[116:119], v[190:193], v[56:59]
	v_mfma_f32_16x16x32_f16 v[44:47], v[108:111], v[198:201], v[44:47]
	v_mfma_f32_16x16x32_f16 v[40:43], v[116:119], v[198:201], v[40:43]
	v_mfma_f32_16x16x32_f16 v[28:31], v[108:111], v[210:213], v[28:31]
	v_mfma_f32_16x16x32_f16 v[24:27], v[116:119], v[210:213], v[24:27]
	v_mfma_f32_16x16x32_f16 v[12:15], v[108:111], v[218:221], v[12:15]
	v_mfma_f32_16x16x32_f16 v[8:11], v[116:119], v[218:221], v[8:11]
	v_mfma_f32_16x16x32_f16 v[52:55], v[160:163], v[186:189], v[52:55]
	v_mfma_f32_16x16x32_f16 v[48:51], v[178:181], v[186:189], v[48:51]
	v_mfma_f32_16x16x32_f16 v[36:39], v[160:163], v[194:197], v[36:39]
	v_mfma_f32_16x16x32_f16 v[32:35], v[178:181], v[194:197], v[32:35]
	v_mfma_f32_16x16x32_f16 v[20:23], v[160:163], v[206:209], v[20:23]
	v_mfma_f32_16x16x32_f16 v[16:19], v[178:181], v[206:209], v[16:19]
	v_mfma_f32_16x16x32_f16 v[4:7], v[160:163], v[214:217], v[4:7]
	v_mfma_f32_16x16x32_f16 v[0:3], v[178:181], v[214:217], v[0:3]
	v_mfma_f32_16x16x32_f16 v[52:55], v[164:167], v[190:193], v[52:55]
	v_mfma_f32_16x16x32_f16 v[48:51], v[182:185], v[190:193], v[48:51]
	v_mfma_f32_16x16x32_f16 v[36:39], v[164:167], v[198:201], v[36:39]
	v_mfma_f32_16x16x32_f16 v[32:35], v[182:185], v[198:201], v[32:35]
	v_mfma_f32_16x16x32_f16 v[20:23], v[164:167], v[210:213], v[20:23]
	v_mfma_f32_16x16x32_f16 v[16:19], v[182:185], v[210:213], v[16:19]
	v_mfma_f32_16x16x32_f16 v[4:7], v[164:167], v[218:221], v[4:7]
	v_mfma_f32_16x16x32_f16 v[0:3], v[182:185], v[218:221], v[0:3]
	s_barrier
	s_add_i32 s68, 0, 0x18000
	s_add_i32 s69, 0, 0x1c000
	v_add_u32_e32 v116, s68, v169
	v_add_u32_e32 v177, s69, v169
	ds_read_b128 v[104:107], v116
	ds_read_b128 v[108:111], v116 offset:1024
	ds_read_b128 v[112:115], v116 offset:2048
	ds_read_b128 v[116:119], v116 offset:3072
	ds_read_b128 v[160:163], v177
	ds_read_b128 v[164:167], v177 offset:1024
	ds_read_b128 v[178:181], v177 offset:2048
	ds_read_b128 v[182:185], v177 offset:3072
	s_add_u32 s34, s34, 0x40000
	s_addc_u32 s35, s35, 0
	s_mov_b32 m0, s46
	s_nop 0
	ds_read_b128 v[186:189], v173 offset:32768
	ds_read_b128 v[190:193], v173 offset:33792
	ds_read_b128 v[194:197], v173 offset:34816
	ds_read_b128 v[198:201], v173 offset:35840
	ds_read_b128 v[206:209], v173 offset:36864
	ds_read_b128 v[210:213], v173 offset:37888
	ds_read_b128 v[214:217], v173 offset:38912
	ds_read_b128 v[218:221], v173 offset:39936
	global_load_lds_dwordx4 v144, s[34:35]
	s_nop 0
	s_mov_b32 m0, s47
	s_nop 0
	global_load_lds_dwordx4 v148, s[34:35]
	s_waitcnt vmcnt(8)
	s_waitcnt lgkmcnt(0)
	s_barrier
	s_waitcnt lgkmcnt(0)
	v_mfma_f32_16x16x32_f16 v[140:143], v[104:107], v[186:189], v[140:143]
	v_mfma_f32_16x16x32_f16 v[136:139], v[112:115], v[186:189], v[136:139]
	v_mfma_f32_16x16x32_f16 v[124:127], v[104:107], v[194:197], v[124:127]
	v_mfma_f32_16x16x32_f16 v[120:123], v[112:115], v[194:197], v[120:123]
	v_mfma_f32_16x16x32_f16 v[92:95], v[104:107], v[206:209], v[92:95]
	v_mfma_f32_16x16x32_f16 v[88:91], v[112:115], v[206:209], v[88:91]
	v_mfma_f32_16x16x32_f16 v[76:79], v[104:107], v[214:217], v[76:79]
	v_mfma_f32_16x16x32_f16 v[72:75], v[112:115], v[214:217], v[72:75]
	v_mfma_f32_16x16x32_f16 v[140:143], v[108:111], v[190:193], v[140:143]
	v_mfma_f32_16x16x32_f16 v[136:139], v[116:119], v[190:193], v[136:139]
	v_mfma_f32_16x16x32_f16 v[124:127], v[108:111], v[198:201], v[124:127]
	v_mfma_f32_16x16x32_f16 v[120:123], v[116:119], v[198:201], v[120:123]
	v_mfma_f32_16x16x32_f16 v[92:95], v[108:111], v[210:213], v[92:95]
	v_mfma_f32_16x16x32_f16 v[88:91], v[116:119], v[210:213], v[88:91]
	v_mfma_f32_16x16x32_f16 v[76:79], v[108:111], v[218:221], v[76:79]
	v_mfma_f32_16x16x32_f16 v[72:75], v[116:119], v[218:221], v[72:75]
	v_mfma_f32_16x16x32_f16 v[132:135], v[160:163], v[186:189], v[132:135]
	v_mfma_f32_16x16x32_f16 v[128:131], v[178:181], v[186:189], v[128:131]
	v_mfma_f32_16x16x32_f16 v[100:103], v[160:163], v[194:197], v[100:103]
	v_mfma_f32_16x16x32_f16 v[96:99], v[178:181], v[194:197], v[96:99]
	v_mfma_f32_16x16x32_f16 v[84:87], v[160:163], v[206:209], v[84:87]
	v_mfma_f32_16x16x32_f16 v[80:83], v[178:181], v[206:209], v[80:83]
	v_mfma_f32_16x16x32_f16 v[68:71], v[160:163], v[214:217], v[68:71]
	v_mfma_f32_16x16x32_f16 v[64:67], v[178:181], v[214:217], v[64:67]
	v_mfma_f32_16x16x32_f16 v[132:135], v[164:167], v[190:193], v[132:135]
	v_mfma_f32_16x16x32_f16 v[128:131], v[182:185], v[190:193], v[128:131]
	v_mfma_f32_16x16x32_f16 v[100:103], v[164:167], v[198:201], v[100:103]
	v_mfma_f32_16x16x32_f16 v[96:99], v[182:185], v[198:201], v[96:99]
	v_mfma_f32_16x16x32_f16 v[84:87], v[164:167], v[210:213], v[84:87]
	v_mfma_f32_16x16x32_f16 v[80:83], v[182:185], v[210:213], v[80:83]
	v_mfma_f32_16x16x32_f16 v[68:71], v[164:167], v[218:221], v[68:71]
	v_mfma_f32_16x16x32_f16 v[64:67], v[182:185], v[218:221], v[64:67]
	s_barrier
	s_add_i32 s34, s68, s44
	v_lshl_add_u64 v[202:203], v[202:203], 0, s[10:11]
	s_mov_b32 m0, s34
	ds_read_b128 v[186:189], v173 offset:49152
	ds_read_b128 v[190:193], v173 offset:50176
	ds_read_b128 v[194:197], v173 offset:51200
	ds_read_b128 v[198:201], v173 offset:52224
	ds_read_b128 v[206:209], v173 offset:53248
	ds_read_b128 v[210:213], v173 offset:54272
	ds_read_b128 v[214:217], v173 offset:55296
	ds_read_b128 v[218:221], v173 offset:56320
	global_load_lds_dwordx4 v[202:203], off
	s_add_i32 m0, s34, 0x2000
	s_add_u32 s26, s26, 0x40080
	v_lshl_add_u64 v[202:203], v[222:223], 0, s[10:11]
	s_addc_u32 s27, s27, 0
	s_add_i32 s34, s69, s44
	global_load_lds_dwordx4 v[202:203], off
	s_nop 0
	s_mov_b32 m0, s34
	s_nop 0
	global_load_lds_dwordx4 v146, s[26:27]
	s_nop 0
	s_add_i32 m0, s34, 0x2000
	s_nop 0
	global_load_lds_dwordx4 v150, s[26:27]
	v_lshl_add_u64 v[202:203], v[224:225], 0, s[10:11]
	s_mov_b32 m0, s55
	s_nop 0
	global_load_lds_dwordx4 v[202:203], off
	v_lshl_add_u64 v[202:203], v[226:227], 0, s[10:11]
	s_mov_b32 m0, s56
	s_nop 0
	global_load_lds_dwordx4 v[202:203], off
	s_waitcnt vmcnt(8)
	s_waitcnt lgkmcnt(0)
	s_barrier
	s_waitcnt lgkmcnt(0)
	v_mfma_f32_16x16x32_f16 v[60:63], v[104:107], v[186:189], v[60:63]
	v_mfma_f32_16x16x32_f16 v[56:59], v[112:115], v[186:189], v[56:59]
	v_mfma_f32_16x16x32_f16 v[44:47], v[104:107], v[194:197], v[44:47]
	v_mfma_f32_16x16x32_f16 v[40:43], v[112:115], v[194:197], v[40:43]
	v_mfma_f32_16x16x32_f16 v[28:31], v[104:107], v[206:209], v[28:31]
	v_mfma_f32_16x16x32_f16 v[24:27], v[112:115], v[206:209], v[24:27]
	v_mfma_f32_16x16x32_f16 v[12:15], v[104:107], v[214:217], v[12:15]
	v_mfma_f32_16x16x32_f16 v[8:11], v[112:115], v[214:217], v[8:11]
	v_mfma_f32_16x16x32_f16 v[60:63], v[108:111], v[190:193], v[60:63]
	v_mfma_f32_16x16x32_f16 v[56:59], v[116:119], v[190:193], v[56:59]
	v_mfma_f32_16x16x32_f16 v[44:47], v[108:111], v[198:201], v[44:47]
	v_mfma_f32_16x16x32_f16 v[40:43], v[116:119], v[198:201], v[40:43]
	v_mfma_f32_16x16x32_f16 v[28:31], v[108:111], v[210:213], v[28:31]
	v_mfma_f32_16x16x32_f16 v[24:27], v[116:119], v[210:213], v[24:27]
	v_mfma_f32_16x16x32_f16 v[12:15], v[108:111], v[218:221], v[12:15]
	v_mfma_f32_16x16x32_f16 v[8:11], v[116:119], v[218:221], v[8:11]
	v_mfma_f32_16x16x32_f16 v[52:55], v[160:163], v[186:189], v[52:55]
	v_mfma_f32_16x16x32_f16 v[48:51], v[178:181], v[186:189], v[48:51]
	v_mfma_f32_16x16x32_f16 v[36:39], v[160:163], v[194:197], v[36:39]
	v_mfma_f32_16x16x32_f16 v[32:35], v[178:181], v[194:197], v[32:35]
	v_mfma_f32_16x16x32_f16 v[20:23], v[160:163], v[206:209], v[20:23]
	v_mfma_f32_16x16x32_f16 v[16:19], v[178:181], v[206:209], v[16:19]
	v_mfma_f32_16x16x32_f16 v[4:7], v[160:163], v[214:217], v[4:7]
	v_mfma_f32_16x16x32_f16 v[0:3], v[178:181], v[214:217], v[0:3]
	v_mfma_f32_16x16x32_f16 v[52:55], v[164:167], v[190:193], v[52:55]
	v_mfma_f32_16x16x32_f16 v[48:51], v[182:185], v[190:193], v[48:51]
	v_mfma_f32_16x16x32_f16 v[36:39], v[164:167], v[198:201], v[36:39]
	v_mfma_f32_16x16x32_f16 v[32:35], v[182:185], v[198:201], v[32:35]
	v_mfma_f32_16x16x32_f16 v[20:23], v[164:167], v[210:213], v[20:23]
	v_mfma_f32_16x16x32_f16 v[16:19], v[182:185], v[210:213], v[16:19]
	v_mfma_f32_16x16x32_f16 v[4:7], v[164:167], v[218:221], v[4:7]
	v_mfma_f32_16x16x32_f16 v[0:3], v[182:185], v[218:221], v[0:3]
	s_barrier
	s_add_i32 s67, s67, 2
	s_add_u32 s24, s24, 0x100
	s_addc_u32 s25, s25, 0
	s_add_u32 s65, s65, 0x100
	s_addc_u32 s66, s66, 0
	s_cmp_gt_u32 s67, 13
	s_cbranch_scc0 .LBB0_873
	s_and_b64 vcc, exec, s[12:13]
	s_cbranch_vccz .LBB0_876
	s_barrier

.LBB0_1584:
	s_ashr_i32 s17, s16, 31
	s_lshl_b64 s[18:19], s[16:17], 19
	s_add_u32 s18, s42, s18
	s_addc_u32 s19, s43, s19
	s_and_b64 s[20:21], s[2:3], exec
	s_cselect_b32 s17, s19, s25
	s_cselect_b32 s60, s18, s24
	s_ashr_i32 s15, s14, 31
	s_lshl_b64 s[20:21], s[14:15], 19
	s_add_u32 s20, s33, s20
	s_addc_u32 s21, s40, s21
	s_and_b64 s[34:35], s[2:3], exec
	s_cselect_b32 s15, s21, s27
	s_cselect_b32 s61, s20, s26
	s_add_u32 s24, s24, 0x40080
	s_addc_u32 s25, s25, 0
	s_add_u32 s62, s26, 0x100
	s_addc_u32 s63, s27, 0
	s_mov_b32 s64, -2
	ds_read_b128 v[104:107], v171
	ds_read_b128 v[108:111], v171 offset:1024
	ds_read_b128 v[112:115], v171 offset:2048
	ds_read_b128 v[116:119], v171 offset:3072
	ds_read_b128 v[160:163], v172
	ds_read_b128 v[164:167], v172 offset:1024
	ds_read_b128 v[178:181], v172 offset:2048
	ds_read_b128 v[182:185], v172 offset:3072
	s_add_u32 s26, s24, 0xfffc0080
	s_addc_u32 s27, s25, -1
	s_cmp_eq_u32 s64, 12
	s_cselect_b32 s35, s17, s27
	s_cselect_b32 s34, s60, s26
	s_cselect_b32 s27, s15, s63
	s_cselect_b32 s26, s61, s62
	v_lshl_add_u64 v[202:203], s[24:25], 0, v[152:153]
	s_add_i32 m0, s23, 0xc000
	ds_read_b128 v[186:189], v173
	ds_read_b128 v[190:193], v173 offset:1024
	ds_read_b128 v[194:197], v173 offset:2048
	ds_read_b128 v[198:201], v173 offset:3072
	ds_read_b128 v[206:209], v173 offset:4096
	ds_read_b128 v[210:213], v173 offset:5120
	ds_read_b128 v[214:217], v173 offset:6144
	ds_read_b128 v[218:221], v173 offset:7168
	global_load_lds_dwordx4 v[202:203], off
	v_lshl_add_u64 v[202:203], s[24:25], 0, v[154:155]
	s_add_i32 m0, s23, 0xe000
	s_nop 0
	global_load_lds_dwordx4 v[202:203], off
	s_waitcnt vmcnt(8)
	s_waitcnt lgkmcnt(0)
	s_barrier
	s_waitcnt lgkmcnt(0)
	v_mfma_f32_16x16x32_f16 v[140:143], v[104:107], v[186:189], 0
	v_mfma_f32_16x16x32_f16 v[136:139], v[112:115], v[186:189], 0
	v_mfma_f32_16x16x32_f16 v[124:127], v[104:107], v[194:197], 0
	v_mfma_f32_16x16x32_f16 v[120:123], v[112:115], v[194:197], 0
	v_mfma_f32_16x16x32_f16 v[92:95], v[104:107], v[206:209], 0
	v_mfma_f32_16x16x32_f16 v[88:91], v[112:115], v[206:209], 0
	v_mfma_f32_16x16x32_f16 v[76:79], v[104:107], v[214:217], 0
	v_mfma_f32_16x16x32_f16 v[72:75], v[112:115], v[214:217], 0
	v_mfma_f32_16x16x32_f16 v[140:143], v[108:111], v[190:193], v[140:143]
	v_mfma_f32_16x16x32_f16 v[136:139], v[116:119], v[190:193], v[136:139]
	v_mfma_f32_16x16x32_f16 v[124:127], v[108:111], v[198:201], v[124:127]
	v_mfma_f32_16x16x32_f16 v[120:123], v[116:119], v[198:201], v[120:123]
	v_mfma_f32_16x16x32_f16 v[92:95], v[108:111], v[210:213], v[92:95]
	v_mfma_f32_16x16x32_f16 v[88:91], v[116:119], v[210:213], v[88:91]
	v_mfma_f32_16x16x32_f16 v[76:79], v[108:111], v[218:221], v[76:79]
	v_mfma_f32_16x16x32_f16 v[72:75], v[116:119], v[218:221], v[72:75]
	v_mfma_f32_16x16x32_f16 v[132:135], v[160:163], v[186:189], 0
	v_mfma_f32_16x16x32_f16 v[128:131], v[178:181], v[186:189], 0
	v_mfma_f32_16x16x32_f16 v[100:103], v[160:163], v[194:197], 0
	v_mfma_f32_16x16x32_f16 v[96:99], v[178:181], v[194:197], 0
	v_mfma_f32_16x16x32_f16 v[84:87], v[160:163], v[206:209], 0
	v_mfma_f32_16x16x32_f16 v[80:83], v[178:181], v[206:209], 0
	v_mfma_f32_16x16x32_f16 v[68:71], v[160:163], v[214:217], 0
	v_mfma_f32_16x16x32_f16 v[64:67], v[178:181], v[214:217], 0
	v_mfma_f32_16x16x32_f16 v[132:135], v[164:167], v[190:193], v[132:135]
	v_mfma_f32_16x16x32_f16 v[128:131], v[182:185], v[190:193], v[128:131]
	v_mfma_f32_16x16x32_f16 v[100:103], v[164:167], v[198:201], v[100:103]
	v_mfma_f32_16x16x32_f16 v[96:99], v[182:185], v[198:201], v[96:99]
	v_mfma_f32_16x16x32_f16 v[84:87], v[164:167], v[210:213], v[84:87]
	v_mfma_f32_16x16x32_f16 v[80:83], v[182:185], v[210:213], v[80:83]
	v_mfma_f32_16x16x32_f16 v[68:71], v[164:167], v[218:221], v[68:71]
	v_mfma_f32_16x16x32_f16 v[64:67], v[182:185], v[218:221], v[64:67]
	s_barrier
	s_add_i32 s65, s55, s41
	v_lshl_add_u64 v[202:203], s[26:27], 0, v[148:149]
	s_mov_b32 m0, s65
	ds_read_b128 v[186:189], v173 offset:16384
	ds_read_b128 v[190:193], v173 offset:17408
	ds_read_b128 v[194:197], v173 offset:18432
	ds_read_b128 v[198:201], v173 offset:19456
	ds_read_b128 v[206:209], v173 offset:20480
	ds_read_b128 v[210:213], v173 offset:21504
	ds_read_b128 v[214:217], v173 offset:22528
	ds_read_b128 v[218:221], v173 offset:23552
	global_load_lds_dwordx4 v[202:203], off
	s_add_i32 m0, s65, 0x2000
	s_add_u32 s66, s26, 0x40000
	v_lshl_add_u64 v[222:223], s[26:27], 0, v[144:145]
	s_addc_u32 s67, s27, 0
	s_add_i32 s65, s56, s41
	global_load_lds_dwordx4 v[222:223], off
	v_lshl_add_u64 v[224:225], s[66:67], 0, v[148:149]
	s_mov_b32 m0, s65
	v_lshl_add_u64 v[226:227], s[34:35], 0, v[146:147]
	global_load_lds_dwordx4 v[224:225], off
	v_lshl_add_u64 v[224:225], s[66:67], 0, v[144:145]
	s_add_i32 m0, s65, 0x2000
	s_nop 0
	global_load_lds_dwordx4 v[224:225], off
	v_lshl_add_u64 v[224:225], s[34:35], 0, v[150:151]
	s_mov_b32 m0, s23
	s_nop 0
	global_load_lds_dwordx4 v[224:225], off
	s_mov_b32 m0, s46
	s_nop 0
	global_load_lds_dwordx4 v[226:227], off
	s_waitcnt vmcnt(8)
	s_waitcnt lgkmcnt(0)
	s_barrier
	s_waitcnt lgkmcnt(0)
	v_mfma_f32_16x16x32_f16 v[60:63], v[104:107], v[186:189], 0
	v_mfma_f32_16x16x32_f16 v[56:59], v[112:115], v[186:189], 0
	v_mfma_f32_16x16x32_f16 v[44:47], v[104:107], v[194:197], 0
	v_mfma_f32_16x16x32_f16 v[40:43], v[112:115], v[194:197], 0
	v_mfma_f32_16x16x32_f16 v[28:31], v[104:107], v[206:209], 0
	v_mfma_f32_16x16x32_f16 v[24:27], v[112:115], v[206:209], 0
	v_mfma_f32_16x16x32_f16 v[12:15], v[104:107], v[214:217], 0
	v_mfma_f32_16x16x32_f16 v[8:11], v[112:115], v[214:217], 0
	v_mfma_f32_16x16x32_f16 v[60:63], v[108:111], v[190:193], v[60:63]
	v_mfma_f32_16x16x32_f16 v[56:59], v[116:119], v[190:193], v[56:59]
	v_mfma_f32_16x16x32_f16 v[44:47], v[108:111], v[198:201], v[44:47]
	v_mfma_f32_16x16x32_f16 v[40:43], v[116:119], v[198:201], v[40:43]
	v_mfma_f32_16x16x32_f16 v[28:31], v[108:111], v[210:213], v[28:31]
	v_mfma_f32_16x16x32_f16 v[24:27], v[116:119], v[210:213], v[24:27]
	v_mfma_f32_16x16x32_f16 v[12:15], v[108:111], v[218:221], v[12:15]
	v_mfma_f32_16x16x32_f16 v[8:11], v[116:119], v[218:221], v[8:11]
	v_mfma_f32_16x16x32_f16 v[52:55], v[160:163], v[186:189], 0
	v_mfma_f32_16x16x32_f16 v[48:51], v[178:181], v[186:189], 0
	v_mfma_f32_16x16x32_f16 v[36:39], v[160:163], v[194:197], 0
	v_mfma_f32_16x16x32_f16 v[32:35], v[178:181], v[194:197], 0
	v_mfma_f32_16x16x32_f16 v[20:23], v[160:163], v[206:209], 0
	v_mfma_f32_16x16x32_f16 v[16:19], v[178:181], v[206:209], 0
	v_mfma_f32_16x16x32_f16 v[4:7], v[160:163], v[214:217], 0
	v_mfma_f32_16x16x32_f16 v[0:3], v[178:181], v[214:217], 0
	v_mfma_f32_16x16x32_f16 v[52:55], v[164:167], v[190:193], v[52:55]
	v_mfma_f32_16x16x32_f16 v[48:51], v[182:185], v[190:193], v[48:51]
	v_mfma_f32_16x16x32_f16 v[36:39], v[164:167], v[198:201], v[36:39]
	v_mfma_f32_16x16x32_f16 v[32:35], v[182:185], v[198:201], v[32:35]
	v_mfma_f32_16x16x32_f16 v[20:23], v[164:167], v[210:213], v[20:23]
	v_mfma_f32_16x16x32_f16 v[16:19], v[182:185], v[210:213], v[16:19]
	v_mfma_f32_16x16x32_f16 v[4:7], v[164:167], v[218:221], v[4:7]
	v_mfma_f32_16x16x32_f16 v[0:3], v[182:185], v[218:221], v[0:3]
	s_barrier
	s_add_i32 s65, 0, 0x18000
	s_add_i32 s66, 0, 0x1c000
	v_add_u32_e32 v116, s65, v169
	v_add_u32_e32 v177, s66, v169
	ds_read_b128 v[104:107], v116
	ds_read_b128 v[108:111], v116 offset:1024
	ds_read_b128 v[112:115], v116 offset:2048
	ds_read_b128 v[116:119], v116 offset:3072
	ds_read_b128 v[160:163], v177
	ds_read_b128 v[164:167], v177 offset:1024
	ds_read_b128 v[178:181], v177 offset:2048
	ds_read_b128 v[182:185], v177 offset:3072
	s_add_u32 s34, s34, 0x40000
	s_addc_u32 s35, s35, 0
	s_mov_b32 m0, s47
	v_lshl_add_u64 v[228:229], s[34:35], 0, v[150:151]
	ds_read_b128 v[186:189], v173 offset:32768
	ds_read_b128 v[190:193], v173 offset:33792
	ds_read_b128 v[194:197], v173 offset:34816
	ds_read_b128 v[198:201], v173 offset:35840
	ds_read_b128 v[206:209], v173 offset:36864
	ds_read_b128 v[210:213], v173 offset:37888
	ds_read_b128 v[214:217], v173 offset:38912
	ds_read_b128 v[218:221], v173 offset:39936
	global_load_lds_dwordx4 v[228:229], off
	v_lshl_add_u64 v[228:229], s[34:35], 0, v[146:147]
	s_mov_b32 m0, s48
	s_nop 0
	global_load_lds_dwordx4 v[228:229], off
	s_waitcnt vmcnt(8)
	s_waitcnt lgkmcnt(0)
	s_barrier
	s_waitcnt lgkmcnt(0)
	v_mfma_f32_16x16x32_f16 v[140:143], v[104:107], v[186:189], v[140:143]
	v_mfma_f32_16x16x32_f16 v[136:139], v[112:115], v[186:189], v[136:139]
	v_mfma_f32_16x16x32_f16 v[124:127], v[104:107], v[194:197], v[124:127]
	v_mfma_f32_16x16x32_f16 v[120:123], v[112:115], v[194:197], v[120:123]
	v_mfma_f32_16x16x32_f16 v[92:95], v[104:107], v[206:209], v[92:95]
	v_mfma_f32_16x16x32_f16 v[88:91], v[112:115], v[206:209], v[88:91]
	v_mfma_f32_16x16x32_f16 v[76:79], v[104:107], v[214:217], v[76:79]
	v_mfma_f32_16x16x32_f16 v[72:75], v[112:115], v[214:217], v[72:75]
	v_mfma_f32_16x16x32_f16 v[140:143], v[108:111], v[190:193], v[140:143]
	v_mfma_f32_16x16x32_f16 v[136:139], v[116:119], v[190:193], v[136:139]
	v_mfma_f32_16x16x32_f16 v[124:127], v[108:111], v[198:201], v[124:127]
	v_mfma_f32_16x16x32_f16 v[120:123], v[116:119], v[198:201], v[120:123]
	v_mfma_f32_16x16x32_f16 v[92:95], v[108:111], v[210:213], v[92:95]
	v_mfma_f32_16x16x32_f16 v[88:91], v[116:119], v[210:213], v[88:91]
	v_mfma_f32_16x16x32_f16 v[76:79], v[108:111], v[218:221], v[76:79]
	v_mfma_f32_16x16x32_f16 v[72:75], v[116:119], v[218:221], v[72:75]
	v_mfma_f32_16x16x32_f16 v[132:135], v[160:163], v[186:189], v[132:135]
	v_mfma_f32_16x16x32_f16 v[128:131], v[178:181], v[186:189], v[128:131]
	v_mfma_f32_16x16x32_f16 v[100:103], v[160:163], v[194:197], v[100:103]
	v_mfma_f32_16x16x32_f16 v[96:99], v[178:181], v[194:197], v[96:99]
	v_mfma_f32_16x16x32_f16 v[84:87], v[160:163], v[206:209], v[84:87]
	v_mfma_f32_16x16x32_f16 v[80:83], v[178:181], v[206:209], v[80:83]
	v_mfma_f32_16x16x32_f16 v[68:71], v[160:163], v[214:217], v[68:71]
	v_mfma_f32_16x16x32_f16 v[64:67], v[178:181], v[214:217], v[64:67]
	v_mfma_f32_16x16x32_f16 v[132:135], v[164:167], v[190:193], v[132:135]
	v_mfma_f32_16x16x32_f16 v[128:131], v[182:185], v[190:193], v[128:131]
	v_mfma_f32_16x16x32_f16 v[100:103], v[164:167], v[198:201], v[100:103]
	v_mfma_f32_16x16x32_f16 v[96:99], v[182:185], v[198:201], v[96:99]
	v_mfma_f32_16x16x32_f16 v[84:87], v[164:167], v[210:213], v[84:87]
	v_mfma_f32_16x16x32_f16 v[80:83], v[182:185], v[210:213], v[80:83]
	v_mfma_f32_16x16x32_f16 v[68:71], v[164:167], v[218:221], v[68:71]
	v_mfma_f32_16x16x32_f16 v[64:67], v[182:185], v[218:221], v[64:67]
	s_barrier
	s_add_i32 s34, s65, s41
	v_lshl_add_u64 v[202:203], v[202:203], 0, s[10:11]
	s_mov_b32 m0, s34
	ds_read_b128 v[186:189], v173 offset:49152
	ds_read_b128 v[190:193], v173 offset:50176
	ds_read_b128 v[194:197], v173 offset:51200
	ds_read_b128 v[198:201], v173 offset:52224
	ds_read_b128 v[206:209], v173 offset:53248
	ds_read_b128 v[210:213], v173 offset:54272
	ds_read_b128 v[214:217], v173 offset:55296
	ds_read_b128 v[218:221], v173 offset:56320
	global_load_lds_dwordx4 v[202:203], off
	s_add_i32 m0, s34, 0x2000
	s_add_u32 s26, s26, 0x40080
	v_lshl_add_u64 v[202:203], v[222:223], 0, s[10:11]
	s_addc_u32 s27, s27, 0
	s_add_i32 s34, s66, s41
	global_load_lds_dwordx4 v[202:203], off
	s_nop 0
	s_mov_b32 m0, s34
	s_nop 0
	global_load_lds_dwordx4 v148, s[26:27]
	s_nop 0
	s_add_i32 m0, s34, 0x2000
	s_nop 0
	global_load_lds_dwordx4 v144, s[26:27]
	v_lshl_add_u64 v[202:203], v[224:225], 0, s[10:11]
	s_mov_b32 m0, s52
	s_nop 0
	global_load_lds_dwordx4 v[202:203], off
	v_lshl_add_u64 v[202:203], v[226:227], 0, s[10:11]
	s_mov_b32 m0, s53
	s_nop 0
	global_load_lds_dwordx4 v[202:203], off
	s_waitcnt vmcnt(8)
	s_waitcnt lgkmcnt(0)
	s_barrier
	s_waitcnt lgkmcnt(0)
	v_mfma_f32_16x16x32_f16 v[60:63], v[104:107], v[186:189], v[60:63]
	v_mfma_f32_16x16x32_f16 v[56:59], v[112:115], v[186:189], v[56:59]
	v_mfma_f32_16x16x32_f16 v[44:47], v[104:107], v[194:197], v[44:47]
	v_mfma_f32_16x16x32_f16 v[40:43], v[112:115], v[194:197], v[40:43]
	v_mfma_f32_16x16x32_f16 v[28:31], v[104:107], v[206:209], v[28:31]
	v_mfma_f32_16x16x32_f16 v[24:27], v[112:115], v[206:209], v[24:27]
	v_mfma_f32_16x16x32_f16 v[12:15], v[104:107], v[214:217], v[12:15]
	v_mfma_f32_16x16x32_f16 v[8:11], v[112:115], v[214:217], v[8:11]
	v_mfma_f32_16x16x32_f16 v[60:63], v[108:111], v[190:193], v[60:63]
	v_mfma_f32_16x16x32_f16 v[56:59], v[116:119], v[190:193], v[56:59]
	v_mfma_f32_16x16x32_f16 v[44:47], v[108:111], v[198:201], v[44:47]
	v_mfma_f32_16x16x32_f16 v[40:43], v[116:119], v[198:201], v[40:43]
	v_mfma_f32_16x16x32_f16 v[28:31], v[108:111], v[210:213], v[28:31]
	v_mfma_f32_16x16x32_f16 v[24:27], v[116:119], v[210:213], v[24:27]
	v_mfma_f32_16x16x32_f16 v[12:15], v[108:111], v[218:221], v[12:15]
	v_mfma_f32_16x16x32_f16 v[8:11], v[116:119], v[218:221], v[8:11]
	v_mfma_f32_16x16x32_f16 v[52:55], v[160:163], v[186:189], v[52:55]
	v_mfma_f32_16x16x32_f16 v[48:51], v[178:181], v[186:189], v[48:51]
	v_mfma_f32_16x16x32_f16 v[36:39], v[160:163], v[194:197], v[36:39]
	v_mfma_f32_16x16x32_f16 v[32:35], v[178:181], v[194:197], v[32:35]
	v_mfma_f32_16x16x32_f16 v[20:23], v[160:163], v[206:209], v[20:23]
	v_mfma_f32_16x16x32_f16 v[16:19], v[178:181], v[206:209], v[16:19]
	v_mfma_f32_16x16x32_f16 v[4:7], v[160:163], v[214:217], v[4:7]
	v_mfma_f32_16x16x32_f16 v[0:3], v[178:181], v[214:217], v[0:3]
	v_mfma_f32_16x16x32_f16 v[52:55], v[164:167], v[190:193], v[52:55]
	v_mfma_f32_16x16x32_f16 v[48:51], v[182:185], v[190:193], v[48:51]
	v_mfma_f32_16x16x32_f16 v[36:39], v[164:167], v[198:201], v[36:39]
	v_mfma_f32_16x16x32_f16 v[32:35], v[182:185], v[198:201], v[32:35]
	v_mfma_f32_16x16x32_f16 v[20:23], v[164:167], v[210:213], v[20:23]
	v_mfma_f32_16x16x32_f16 v[16:19], v[182:185], v[210:213], v[16:19]
	v_mfma_f32_16x16x32_f16 v[4:7], v[164:167], v[218:221], v[4:7]
	v_mfma_f32_16x16x32_f16 v[0:3], v[182:185], v[218:221], v[0:3]
	s_barrier
	s_add_i32 s64, s64, 2
	s_add_u32 s24, s24, 0x100
	s_addc_u32 s25, s25, 0
	s_add_u32 s62, s62, 0x100
	s_addc_u32 s63, s63, 0
	s_cmp_gt_u32 s64, 13
.LBB0_1585:
	ds_read_b128 v[104:107], v171
	ds_read_b128 v[108:111], v171 offset:1024
	ds_read_b128 v[112:115], v171 offset:2048
	ds_read_b128 v[116:119], v171 offset:3072
	ds_read_b128 v[160:163], v172
	ds_read_b128 v[164:167], v172 offset:1024
	ds_read_b128 v[178:181], v172 offset:2048
	ds_read_b128 v[182:185], v172 offset:3072
	s_add_u32 s26, s24, 0xfffc0080
	s_addc_u32 s27, s25, -1
	s_cmp_eq_u32 s64, 12
	s_cselect_b32 s35, s17, s27
	s_cselect_b32 s34, s60, s26
	s_cselect_b32 s27, s15, s63
	s_cselect_b32 s26, s61, s62
	s_nop 0
	s_add_i32 m0, s23, 0xc000
	ds_read_b128 v[186:189], v173
	ds_read_b128 v[190:193], v173 offset:1024
	ds_read_b128 v[194:197], v173 offset:2048
	ds_read_b128 v[198:201], v173 offset:3072
	ds_read_b128 v[206:209], v173 offset:4096
	ds_read_b128 v[210:213], v173 offset:5120
	ds_read_b128 v[214:217], v173 offset:6144
	ds_read_b128 v[218:221], v173 offset:7168
	global_load_lds_dwordx4 v152, s[24:25]
	s_nop 0
	s_add_i32 m0, s23, 0xe000
	s_nop 0
	global_load_lds_dwordx4 v154, s[24:25]
	s_waitcnt vmcnt(8)
	s_waitcnt lgkmcnt(0)
	s_barrier
	s_waitcnt lgkmcnt(0)
	v_mfma_f32_16x16x32_f16 v[140:143], v[104:107], v[186:189], v[140:143]
	v_mfma_f32_16x16x32_f16 v[136:139], v[112:115], v[186:189], v[136:139]
	v_mfma_f32_16x16x32_f16 v[124:127], v[104:107], v[194:197], v[124:127]
	v_mfma_f32_16x16x32_f16 v[120:123], v[112:115], v[194:197], v[120:123]
	v_mfma_f32_16x16x32_f16 v[92:95], v[104:107], v[206:209], v[92:95]
	v_mfma_f32_16x16x32_f16 v[88:91], v[112:115], v[206:209], v[88:91]
	v_mfma_f32_16x16x32_f16 v[76:79], v[104:107], v[214:217], v[76:79]
	v_mfma_f32_16x16x32_f16 v[72:75], v[112:115], v[214:217], v[72:75]
	v_mfma_f32_16x16x32_f16 v[140:143], v[108:111], v[190:193], v[140:143]
	v_mfma_f32_16x16x32_f16 v[136:139], v[116:119], v[190:193], v[136:139]
	v_mfma_f32_16x16x32_f16 v[124:127], v[108:111], v[198:201], v[124:127]
	v_mfma_f32_16x16x32_f16 v[120:123], v[116:119], v[198:201], v[120:123]
	v_mfma_f32_16x16x32_f16 v[92:95], v[108:111], v[210:213], v[92:95]
	v_mfma_f32_16x16x32_f16 v[88:91], v[116:119], v[210:213], v[88:91]
	v_mfma_f32_16x16x32_f16 v[76:79], v[108:111], v[218:221], v[76:79]
	v_mfma_f32_16x16x32_f16 v[72:75], v[116:119], v[218:221], v[72:75]
	v_mfma_f32_16x16x32_f16 v[132:135], v[160:163], v[186:189], v[132:135]
	v_mfma_f32_16x16x32_f16 v[128:131], v[178:181], v[186:189], v[128:131]
	v_mfma_f32_16x16x32_f16 v[100:103], v[160:163], v[194:197], v[100:103]
	v_mfma_f32_16x16x32_f16 v[96:99], v[178:181], v[194:197], v[96:99]
	v_mfma_f32_16x16x32_f16 v[84:87], v[160:163], v[206:209], v[84:87]
	v_mfma_f32_16x16x32_f16 v[80:83], v[178:181], v[206:209], v[80:83]
	v_mfma_f32_16x16x32_f16 v[68:71], v[160:163], v[214:217], v[68:71]
	v_mfma_f32_16x16x32_f16 v[64:67], v[178:181], v[214:217], v[64:67]
	v_mfma_f32_16x16x32_f16 v[132:135], v[164:167], v[190:193], v[132:135]
	v_mfma_f32_16x16x32_f16 v[128:131], v[182:185], v[190:193], v[128:131]
	v_mfma_f32_16x16x32_f16 v[100:103], v[164:167], v[198:201], v[100:103]
	v_mfma_f32_16x16x32_f16 v[96:99], v[182:185], v[198:201], v[96:99]
	v_mfma_f32_16x16x32_f16 v[84:87], v[164:167], v[210:213], v[84:87]
	v_mfma_f32_16x16x32_f16 v[80:83], v[182:185], v[210:213], v[80:83]
	v_mfma_f32_16x16x32_f16 v[68:71], v[164:167], v[218:221], v[68:71]
	v_mfma_f32_16x16x32_f16 v[64:67], v[182:185], v[218:221], v[64:67]
	s_barrier
	s_add_i32 s65, s55, s41
	v_lshl_add_u64 v[202:203], s[26:27], 0, v[148:149]
	s_mov_b32 m0, s65
	ds_read_b128 v[186:189], v173 offset:16384
	ds_read_b128 v[190:193], v173 offset:17408
	ds_read_b128 v[194:197], v173 offset:18432
	ds_read_b128 v[198:201], v173 offset:19456
	ds_read_b128 v[206:209], v173 offset:20480
	ds_read_b128 v[210:213], v173 offset:21504
	ds_read_b128 v[214:217], v173 offset:22528
	ds_read_b128 v[218:221], v173 offset:23552
	global_load_lds_dwordx4 v[202:203], off
	s_add_i32 m0, s65, 0x2000
	s_add_u32 s66, s26, 0x40000
	v_lshl_add_u64 v[222:223], s[26:27], 0, v[144:145]
	s_addc_u32 s67, s27, 0
	s_add_i32 s65, s56, s41
	global_load_lds_dwordx4 v[222:223], off
	s_nop 0
	s_mov_b32 m0, s65
	v_lshl_add_u64 v[226:227], s[34:35], 0, v[146:147]
	global_load_lds_dwordx4 v148, s[66:67]
	s_nop 0
	s_add_i32 m0, s65, 0x2000
	s_nop 0
	global_load_lds_dwordx4 v144, s[66:67]
	v_lshl_add_u64 v[224:225], s[34:35], 0, v[150:151]
	s_mov_b32 m0, s23
	s_nop 0
	global_load_lds_dwordx4 v[224:225], off
	s_mov_b32 m0, s46
	s_nop 0
	global_load_lds_dwordx4 v[226:227], off
	s_waitcnt vmcnt(8)
	s_waitcnt lgkmcnt(0)
	s_barrier
	s_waitcnt lgkmcnt(0)
	v_mfma_f32_16x16x32_f16 v[60:63], v[104:107], v[186:189], v[60:63]
	v_mfma_f32_16x16x32_f16 v[56:59], v[112:115], v[186:189], v[56:59]
	v_mfma_f32_16x16x32_f16 v[44:47], v[104:107], v[194:197], v[44:47]
	v_mfma_f32_16x16x32_f16 v[40:43], v[112:115], v[194:197], v[40:43]
	v_mfma_f32_16x16x32_f16 v[28:31], v[104:107], v[206:209], v[28:31]
	v_mfma_f32_16x16x32_f16 v[24:27], v[112:115], v[206:209], v[24:27]
	v_mfma_f32_16x16x32_f16 v[12:15], v[104:107], v[214:217], v[12:15]
	v_mfma_f32_16x16x32_f16 v[8:11], v[112:115], v[214:217], v[8:11]
	v_mfma_f32_16x16x32_f16 v[60:63], v[108:111], v[190:193], v[60:63]
	v_mfma_f32_16x16x32_f16 v[56:59], v[116:119], v[190:193], v[56:59]
	v_mfma_f32_16x16x32_f16 v[44:47], v[108:111], v[198:201], v[44:47]
	v_mfma_f32_16x16x32_f16 v[40:43], v[116:119], v[198:201], v[40:43]
	v_mfma_f32_16x16x32_f16 v[28:31], v[108:111], v[210:213], v[28:31]
	v_mfma_f32_16x16x32_f16 v[24:27], v[116:119], v[210:213], v[24:27]
	v_mfma_f32_16x16x32_f16 v[12:15], v[108:111], v[218:221], v[12:15]
	v_mfma_f32_16x16x32_f16 v[8:11], v[116:119], v[218:221], v[8:11]
	v_mfma_f32_16x16x32_f16 v[52:55], v[160:163], v[186:189], v[52:55]
	v_mfma_f32_16x16x32_f16 v[48:51], v[178:181], v[186:189], v[48:51]
	v_mfma_f32_16x16x32_f16 v[36:39], v[160:163], v[194:197], v[36:39]
	v_mfma_f32_16x16x32_f16 v[32:35], v[178:181], v[194:197], v[32:35]
	v_mfma_f32_16x16x32_f16 v[20:23], v[160:163], v[206:209], v[20:23]
	v_mfma_f32_16x16x32_f16 v[16:19], v[178:181], v[206:209], v[16:19]
	v_mfma_f32_16x16x32_f16 v[4:7], v[160:163], v[214:217], v[4:7]
	v_mfma_f32_16x16x32_f16 v[0:3], v[178:181], v[214:217], v[0:3]
	v_mfma_f32_16x16x32_f16 v[52:55], v[164:167], v[190:193], v[52:55]
	v_mfma_f32_16x16x32_f16 v[48:51], v[182:185], v[190:193], v[48:51]
	v_mfma_f32_16x16x32_f16 v[36:39], v[164:167], v[198:201], v[36:39]
	v_mfma_f32_16x16x32_f16 v[32:35], v[182:185], v[198:201], v[32:35]
	v_mfma_f32_16x16x32_f16 v[20:23], v[164:167], v[210:213], v[20:23]
	v_mfma_f32_16x16x32_f16 v[16:19], v[182:185], v[210:213], v[16:19]
	v_mfma_f32_16x16x32_f16 v[4:7], v[164:167], v[218:221], v[4:7]
	v_mfma_f32_16x16x32_f16 v[0:3], v[182:185], v[218:221], v[0:3]
	s_barrier
	s_add_i32 s65, 0, 0x18000
	s_add_i32 s66, 0, 0x1c000
	v_add_u32_e32 v116, s65, v169
	v_add_u32_e32 v177, s66, v169
	ds_read_b128 v[104:107], v116
	ds_read_b128 v[108:111], v116 offset:1024
	ds_read_b128 v[112:115], v116 offset:2048
	ds_read_b128 v[116:119], v116 offset:3072
	ds_read_b128 v[160:163], v177
	ds_read_b128 v[164:167], v177 offset:1024
	ds_read_b128 v[178:181], v177 offset:2048
	ds_read_b128 v[182:185], v177 offset:3072
	s_add_u32 s34, s34, 0x40000
	s_addc_u32 s35, s35, 0
	s_mov_b32 m0, s47
	s_nop 0
	ds_read_b128 v[186:189], v173 offset:32768
	ds_read_b128 v[190:193], v173 offset:33792
	ds_read_b128 v[194:197], v173 offset:34816
	ds_read_b128 v[198:201], v173 offset:35840
	ds_read_b128 v[206:209], v173 offset:36864
	ds_read_b128 v[210:213], v173 offset:37888
	ds_read_b128 v[214:217], v173 offset:38912
	ds_read_b128 v[218:221], v173 offset:39936
	global_load_lds_dwordx4 v150, s[34:35]
	s_nop 0
	s_mov_b32 m0, s48
	s_nop 0
	global_load_lds_dwordx4 v146, s[34:35]
	s_waitcnt vmcnt(8)
	s_waitcnt lgkmcnt(0)
	s_barrier
	s_waitcnt lgkmcnt(0)
	v_mfma_f32_16x16x32_f16 v[140:143], v[104:107], v[186:189], v[140:143]
	v_mfma_f32_16x16x32_f16 v[136:139], v[112:115], v[186:189], v[136:139]
	v_mfma_f32_16x16x32_f16 v[124:127], v[104:107], v[194:197], v[124:127]
	v_mfma_f32_16x16x32_f16 v[120:123], v[112:115], v[194:197], v[120:123]
	v_mfma_f32_16x16x32_f16 v[92:95], v[104:107], v[206:209], v[92:95]
	v_mfma_f32_16x16x32_f16 v[88:91], v[112:115], v[206:209], v[88:91]
	v_mfma_f32_16x16x32_f16 v[76:79], v[104:107], v[214:217], v[76:79]
	v_mfma_f32_16x16x32_f16 v[72:75], v[112:115], v[214:217], v[72:75]
	v_mfma_f32_16x16x32_f16 v[140:143], v[108:111], v[190:193], v[140:143]
	v_mfma_f32_16x16x32_f16 v[136:139], v[116:119], v[190:193], v[136:139]
	v_mfma_f32_16x16x32_f16 v[124:127], v[108:111], v[198:201], v[124:127]
	v_mfma_f32_16x16x32_f16 v[120:123], v[116:119], v[198:201], v[120:123]
	v_mfma_f32_16x16x32_f16 v[92:95], v[108:111], v[210:213], v[92:95]
	v_mfma_f32_16x16x32_f16 v[88:91], v[116:119], v[210:213], v[88:91]
	v_mfma_f32_16x16x32_f16 v[76:79], v[108:111], v[218:221], v[76:79]
	v_mfma_f32_16x16x32_f16 v[72:75], v[116:119], v[218:221], v[72:75]
	v_mfma_f32_16x16x32_f16 v[132:135], v[160:163], v[186:189], v[132:135]
	v_mfma_f32_16x16x32_f16 v[128:131], v[178:181], v[186:189], v[128:131]
	v_mfma_f32_16x16x32_f16 v[100:103], v[160:163], v[194:197], v[100:103]
	v_mfma_f32_16x16x32_f16 v[96:99], v[178:181], v[194:197], v[96:99]
	v_mfma_f32_16x16x32_f16 v[84:87], v[160:163], v[206:209], v[84:87]
	v_mfma_f32_16x16x32_f16 v[80:83], v[178:181], v[206:209], v[80:83]
	v_mfma_f32_16x16x32_f16 v[68:71], v[160:163], v[214:217], v[68:71]
	v_mfma_f32_16x16x32_f16 v[64:67], v[178:181], v[214:217], v[64:67]
	v_mfma_f32_16x16x32_f16 v[132:135], v[164:167], v[190:193], v[132:135]
	v_mfma_f32_16x16x32_f16 v[128:131], v[182:185], v[190:193], v[128:131]
	v_mfma_f32_16x16x32_f16 v[100:103], v[164:167], v[198:201], v[100:103]
	v_mfma_f32_16x16x32_f16 v[96:99], v[182:185], v[198:201], v[96:99]
	v_mfma_f32_16x16x32_f16 v[84:87], v[164:167], v[210:213], v[84:87]
	v_mfma_f32_16x16x32_f16 v[80:83], v[182:185], v[210:213], v[80:83]
	v_mfma_f32_16x16x32_f16 v[68:71], v[164:167], v[218:221], v[68:71]
	v_mfma_f32_16x16x32_f16 v[64:67], v[182:185], v[218:221], v[64:67]
	s_barrier
	s_add_i32 s34, s65, s41
	v_lshl_add_u64 v[202:203], v[202:203], 0, s[10:11]
	s_mov_b32 m0, s34
	ds_read_b128 v[186:189], v173 offset:49152
	ds_read_b128 v[190:193], v173 offset:50176
	ds_read_b128 v[194:197], v173 offset:51200
	ds_read_b128 v[198:201], v173 offset:52224
	ds_read_b128 v[206:209], v173 offset:53248
	ds_read_b128 v[210:213], v173 offset:54272
	ds_read_b128 v[214:217], v173 offset:55296
	ds_read_b128 v[218:221], v173 offset:56320
	global_load_lds_dwordx4 v[202:203], off
	s_add_i32 m0, s34, 0x2000
	s_add_u32 s26, s26, 0x40080
	v_lshl_add_u64 v[202:203], v[222:223], 0, s[10:11]
	s_addc_u32 s27, s27, 0
	s_add_i32 s34, s66, s41
	global_load_lds_dwordx4 v[202:203], off
	s_nop 0
	s_mov_b32 m0, s34
	s_nop 0
	global_load_lds_dwordx4 v148, s[26:27]
	s_nop 0
	s_add_i32 m0, s34, 0x2000
	s_nop 0
	global_load_lds_dwordx4 v144, s[26:27]
	v_lshl_add_u64 v[202:203], v[224:225], 0, s[10:11]
	s_mov_b32 m0, s52
	s_nop 0
	global_load_lds_dwordx4 v[202:203], off
	v_lshl_add_u64 v[202:203], v[226:227], 0, s[10:11]
	s_mov_b32 m0, s53
	s_nop 0
	global_load_lds_dwordx4 v[202:203], off
	s_waitcnt vmcnt(8)
	s_waitcnt lgkmcnt(0)
	s_barrier
	s_waitcnt lgkmcnt(0)
	v_mfma_f32_16x16x32_f16 v[60:63], v[104:107], v[186:189], v[60:63]
	v_mfma_f32_16x16x32_f16 v[56:59], v[112:115], v[186:189], v[56:59]
	v_mfma_f32_16x16x32_f16 v[44:47], v[104:107], v[194:197], v[44:47]
	v_mfma_f32_16x16x32_f16 v[40:43], v[112:115], v[194:197], v[40:43]
	v_mfma_f32_16x16x32_f16 v[28:31], v[104:107], v[206:209], v[28:31]
	v_mfma_f32_16x16x32_f16 v[24:27], v[112:115], v[206:209], v[24:27]
	v_mfma_f32_16x16x32_f16 v[12:15], v[104:107], v[214:217], v[12:15]
	v_mfma_f32_16x16x32_f16 v[8:11], v[112:115], v[214:217], v[8:11]
	v_mfma_f32_16x16x32_f16 v[60:63], v[108:111], v[190:193], v[60:63]
	v_mfma_f32_16x16x32_f16 v[56:59], v[116:119], v[190:193], v[56:59]
	v_mfma_f32_16x16x32_f16 v[44:47], v[108:111], v[198:201], v[44:47]
	v_mfma_f32_16x16x32_f16 v[40:43], v[116:119], v[198:201], v[40:43]
	v_mfma_f32_16x16x32_f16 v[28:31], v[108:111], v[210:213], v[28:31]
	v_mfma_f32_16x16x32_f16 v[24:27], v[116:119], v[210:213], v[24:27]
	v_mfma_f32_16x16x32_f16 v[12:15], v[108:111], v[218:221], v[12:15]
	v_mfma_f32_16x16x32_f16 v[8:11], v[116:119], v[218:221], v[8:11]
	v_mfma_f32_16x16x32_f16 v[52:55], v[160:163], v[186:189], v[52:55]
	v_mfma_f32_16x16x32_f16 v[48:51], v[178:181], v[186:189], v[48:51]
	v_mfma_f32_16x16x32_f16 v[36:39], v[160:163], v[194:197], v[36:39]
	v_mfma_f32_16x16x32_f16 v[32:35], v[178:181], v[194:197], v[32:35]
	v_mfma_f32_16x16x32_f16 v[20:23], v[160:163], v[206:209], v[20:23]
	v_mfma_f32_16x16x32_f16 v[16:19], v[178:181], v[206:209], v[16:19]
	v_mfma_f32_16x16x32_f16 v[4:7], v[160:163], v[214:217], v[4:7]
	v_mfma_f32_16x16x32_f16 v[0:3], v[178:181], v[214:217], v[0:3]
	v_mfma_f32_16x16x32_f16 v[52:55], v[164:167], v[190:193], v[52:55]
	v_mfma_f32_16x16x32_f16 v[48:51], v[182:185], v[190:193], v[48:51]
	v_mfma_f32_16x16x32_f16 v[36:39], v[164:167], v[198:201], v[36:39]
	v_mfma_f32_16x16x32_f16 v[32:35], v[182:185], v[198:201], v[32:35]
	v_mfma_f32_16x16x32_f16 v[20:23], v[164:167], v[210:213], v[20:23]
	v_mfma_f32_16x16x32_f16 v[16:19], v[182:185], v[210:213], v[16:19]
	v_mfma_f32_16x16x32_f16 v[4:7], v[164:167], v[218:221], v[4:7]
	v_mfma_f32_16x16x32_f16 v[0:3], v[182:185], v[218:221], v[0:3]
	s_barrier
	s_add_i32 s64, s64, 2
	s_add_u32 s24, s24, 0x100
	s_addc_u32 s25, s25, 0
	s_add_u32 s62, s62, 0x100
	s_addc_u32 s63, s63, 0
	s_cmp_gt_u32 s64, 13
	s_cbranch_scc0 .LBB0_1585
	s_and_b64 vcc, exec, s[12:13]
	s_cbranch_vccz .LBB0_1588
	s_barrier
